# GEMM K-loops: duplicate lgkmcnt(0) after pre-MMA barrier removed; post-MMA barrier signalled 2 MFMAs early in phases 1,3,5,7 (trailing MFMAs at prio 2)
# speedup vs baseline: 1.0293x; 1.0045x over previous
; #define PG8_STAGE(bufoff, gbase, voff) do { _Pragma("unroll") for (int _i = 0; _i < 2; ++_i) \
;         __builtin_amdgcn_global_load_lds((const unsigned*)((const char*)(gbase) + (voff)[_i]), (LAS unsigned*)(lds + (bufoff) + ldsw + _i * 8192), 16, 0, 0); } while (0)
; #define PG8_LDA(dst, b, h) do { _Pragma("unroll") for (int m = 0; m < 4; ++m) _Pragma("unroll") for (int k = 0; k < 2; ++k) dst[m][k] = *(const LAS bf16x8*)(lds + PG8_SA(b, h) + aoff + m * 2048 + k * 1024); } while (0)
; #define PG8_LDB(dst, b, h) do { _Pragma("unroll") for (int n = 0; n < 2; ++n) _Pragma("unroll") for (int k = 0; k < 2; ++k) dst[n][k] = *(const LAS bf16x8*)(lds + PG8_SB(b, h) + boff + n * 2048 + k * 1024); } while (0)
; #define PG8_MMA(ai, bj, At, Bt) do { __builtin_amdgcn_s_setprio(1); _Pragma("unroll") for (int m = 0; m < 4; ++m) _Pragma("unroll") for (int n = 0; n < 2; ++n) _Pragma("unroll") for (int k = 0; k < 2; ++k) \
;         acc[ai][bj][m][n] = __builtin_amdgcn_mfma_f32_16x16x32_bf16(Bt[n][k], At[m][k], acc[ai][bj][m][n], 0, 0, 0); __builtin_amdgcn_s_setprio(0); } while (0)
; #define PG8_WAIT_L(n) asm volatile("s_waitcnt lgkmcnt(" #n ")" ::: "memory")
; #define PG8_BAR __builtin_amdgcn_s_barrier()
; #define PG8_SCHED __builtin_amdgcn_sched_barrier(0)
; template <class Epi, class Sched, int LD>
; __device__ __forceinline__ void gemm_phase(LAS unsigned char* lds, const Gemm g, const Sched& S, const Epi& E) {
;     ...
;         for (int t = 0; t < nt; t += 2) {
;             const bool last = (t == nt - 2);
;             const char* a1 = cA + (size_t)(t + 1) * kstep;
;             const char* a2 = last ? nA : cA + (size_t)(t + 2) * kstep; const char* b2 = last ? nB : cB + (size_t)(t + 2) * kstep;
;             const char* a3 = a2 + kstep; const char* b3 = b2 + kstep;
;             PG8_LDB(B0, 0, 0); PG8_SCHED; PG8_LDA(At, 0, 0); PG8_STAGE(PG8_SA(1, 1), a1 + hstep, voffA);
;             PG8_WAIT_L(8); PG8_BAR; PG8_WAIT_L(0); PG8_MMA(0, 0, At, B0); PG8_BAR; PG8_SCHED;
;             PG8_LDB(B1, 0, 1); PG8_STAGE(PG8_SB(0, 0), b2, voffB);
;             PG8_BAR; PG8_WAIT_L(0); PG8_MMA(0, 1, At, B1); PG8_BAR;
;             PG8_LDA(At, 0, 1); PG8_STAGE(PG8_SA(0, 0), a2, voffA);
;             PG8_BAR; PG8_WAIT_L(0); PG8_MMA(1, 0, At, B0); PG8_BAR; PG8_SCHED;
;             PG8_STAGE(PG8_SB(0, 1), b2 + hstep, voffB);
.LBB0_58:
	s_add_i32 s71, s4, 2
	s_add_u32 s48, s46, 0x4000
	s_addc_u32 s5, s47, 0
	s_cmp_eq_u32 s68, s4
	s_cselect_b32 s4, s42, s48
	s_cselect_b32 s5, s43, s5
	s_cselect_b32 s48, s44, s69
	s_cselect_b32 s49, s45, s70
	s_add_u32 s50, s4, 0x8000
	s_addc_u32 s51, s5, 0
	s_add_i32 s72, 0, 0x10000
	ds_read_b128 v[140:143], v228
	ds_read_b128 v[150:153], v228 offset:1024
	ds_read_b128 v[154:157], v228 offset:2048
	ds_read_b128 v[176:179], v228 offset:3072
	s_add_i32 m0, s39, 0xc000
	ds_read_b128 v[180:183], v148
	ds_read_b128 v[184:187], v148 offset:1024
	ds_read_b128 v[188:191], v148 offset:2048
	ds_read_b128 v[192:195], v148 offset:3072
	ds_read_b128 v[196:199], v148 offset:4096
	ds_read_b128 v[200:203], v148 offset:5120
	ds_read_b128 v[204:207], v148 offset:6144
	ds_read_b128 v[208:211], v148 offset:7168
	global_load_lds_dwordx4 v132, s[46:47]
	s_add_i32 m0, s39, 0xe000
	s_nop 0
	global_load_lds_dwordx4 v138, s[46:47]
	s_waitcnt lgkmcnt(8)
	s_barrier
	s_waitcnt lgkmcnt(0)
	s_setprio 1
	v_mfma_f32_16x16x32_bf16 v[128:131], v[140:143], v[180:183], v[128:131]
	v_mfma_f32_16x16x32_bf16 v[124:127], v[154:157], v[180:183], v[124:127]
	v_mfma_f32_16x16x32_bf16 v[112:115], v[140:143], v[188:191], v[112:115]
	v_mfma_f32_16x16x32_bf16 v[108:111], v[154:157], v[188:191], v[108:111]
	v_mfma_f32_16x16x32_bf16 v[96:99], v[140:143], v[196:199], v[96:99]
	v_mfma_f32_16x16x32_bf16 v[92:95], v[154:157], v[196:199], v[92:95]
	v_mfma_f32_16x16x32_bf16 v[80:83], v[140:143], v[204:207], v[80:83]
	v_mfma_f32_16x16x32_bf16 v[76:79], v[154:157], v[204:207], v[76:79]
	v_mfma_f32_16x16x32_bf16 v[128:131], v[150:153], v[184:187], v[128:131]
	v_mfma_f32_16x16x32_bf16 v[124:127], v[176:179], v[184:187], v[124:127]
	v_mfma_f32_16x16x32_bf16 v[112:115], v[150:153], v[192:195], v[112:115]
	v_mfma_f32_16x16x32_bf16 v[108:111], v[176:179], v[192:195], v[108:111]
	v_mfma_f32_16x16x32_bf16 v[96:99], v[150:153], v[200:203], v[96:99]
	v_mfma_f32_16x16x32_bf16 v[92:95], v[176:179], v[200:203], v[92:95]
	s_setprio 2
	s_barrier
	v_mfma_f32_16x16x32_bf16 v[80:83], v[150:153], v[208:211], v[80:83]
	v_mfma_f32_16x16x32_bf16 v[76:79], v[176:179], v[208:211], v[76:79]
	s_setprio 0
	s_add_i32 s74, 0, 0x14000
	s_add_i32 s72, s72, s29
	ds_read_b128 v[212:215], v228 offset:16384
	ds_read_b128 v[216:219], v228 offset:17408
	ds_read_b128 v[220:223], v228 offset:18432
	ds_read_b128 v[224:227], v228 offset:19456
	s_mov_b32 m0, s72
	s_nop 0
	global_load_lds_dwordx4 v132, s[48:49]
	s_add_i32 m0, s72, 0x2000
	s_nop 0
	global_load_lds_dwordx4 v138, s[48:49]
	s_barrier
	s_waitcnt lgkmcnt(0)
	s_setprio 1
	v_mfma_f32_16x16x32_bf16 v[120:123], v[212:215], v[180:183], v[120:123]
	v_mfma_f32_16x16x32_bf16 v[116:119], v[220:223], v[180:183], v[116:119]
	v_mfma_f32_16x16x32_bf16 v[104:107], v[212:215], v[188:191], v[104:107]
	v_mfma_f32_16x16x32_bf16 v[100:103], v[220:223], v[188:191], v[100:103]
	v_mfma_f32_16x16x32_bf16 v[88:91], v[212:215], v[196:199], v[88:91]
	v_mfma_f32_16x16x32_bf16 v[84:87], v[220:223], v[196:199], v[84:87]
	v_mfma_f32_16x16x32_bf16 v[72:75], v[212:215], v[204:207], v[72:75]
	v_mfma_f32_16x16x32_bf16 v[68:71], v[220:223], v[204:207], v[68:71]
	v_mfma_f32_16x16x32_bf16 v[120:123], v[216:219], v[184:187], v[120:123]
	v_mfma_f32_16x16x32_bf16 v[116:119], v[224:227], v[184:187], v[116:119]
	v_mfma_f32_16x16x32_bf16 v[104:107], v[216:219], v[192:195], v[104:107]
	v_mfma_f32_16x16x32_bf16 v[100:103], v[224:227], v[192:195], v[100:103]
	v_mfma_f32_16x16x32_bf16 v[88:91], v[216:219], v[200:203], v[88:91]
	v_mfma_f32_16x16x32_bf16 v[84:87], v[224:227], v[200:203], v[84:87]
	v_mfma_f32_16x16x32_bf16 v[72:75], v[216:219], v[208:211], v[72:75]
	v_mfma_f32_16x16x32_bf16 v[68:71], v[224:227], v[208:211], v[68:71]
	s_setprio 0
	s_mov_b32 m0, s39
	s_barrier
	ds_read_b128 v[180:183], v148 offset:16384
	ds_read_b128 v[184:187], v148 offset:17408
	ds_read_b128 v[188:191], v148 offset:18432
	ds_read_b128 v[192:195], v148 offset:19456
	ds_read_b128 v[196:199], v148 offset:20480
	ds_read_b128 v[200:203], v148 offset:21504
	ds_read_b128 v[204:207], v148 offset:22528
	ds_read_b128 v[208:211], v148 offset:23552
	global_load_lds_dwordx4 v132, s[4:5]
	s_mov_b32 m0, s52
	s_nop 0
	global_load_lds_dwordx4 v138, s[4:5]
	s_barrier
	s_waitcnt lgkmcnt(0)
	s_setprio 1
	v_mfma_f32_16x16x32_bf16 v[64:67], v[140:143], v[180:183], v[64:67]
	v_mfma_f32_16x16x32_bf16 v[60:63], v[154:157], v[180:183], v[60:63]
	v_mfma_f32_16x16x32_bf16 v[48:51], v[140:143], v[188:191], v[48:51]
	v_mfma_f32_16x16x32_bf16 v[44:47], v[154:157], v[188:191], v[44:47]
	v_mfma_f32_16x16x32_bf16 v[32:35], v[140:143], v[196:199], v[32:35]
	v_mfma_f32_16x16x32_bf16 v[28:31], v[154:157], v[196:199], v[28:31]
	v_mfma_f32_16x16x32_bf16 v[16:19], v[140:143], v[204:207], v[16:19]
	v_mfma_f32_16x16x32_bf16 v[12:15], v[154:157], v[204:207], v[12:15]
	v_mfma_f32_16x16x32_bf16 v[64:67], v[150:153], v[184:187], v[64:67]
	v_mfma_f32_16x16x32_bf16 v[60:63], v[176:179], v[184:187], v[60:63]
	v_mfma_f32_16x16x32_bf16 v[48:51], v[150:153], v[192:195], v[48:51]
	v_mfma_f32_16x16x32_bf16 v[44:47], v[176:179], v[192:195], v[44:47]
	v_mfma_f32_16x16x32_bf16 v[32:35], v[150:153], v[200:203], v[32:35]
	v_mfma_f32_16x16x32_bf16 v[28:31], v[176:179], v[200:203], v[28:31]
	s_setprio 2
	s_barrier
	v_mfma_f32_16x16x32_bf16 v[16:19], v[150:153], v[208:211], v[16:19]
	v_mfma_f32_16x16x32_bf16 v[12:15], v[176:179], v[208:211], v[12:15]
	s_setprio 0
	s_add_u32 s72, s48, 0x4000
	s_addc_u32 s73, s49, 0
	s_add_i32 s74, s74, s29
	s_mov_b32 m0, s74
	s_nop 0
	global_load_lds_dwordx4 v132, s[72:73]
	s_add_i32 m0, s74, 0x2000
	s_nop 0
	global_load_lds_dwordx4 v138, s[72:73]
	s_waitcnt vmcnt(6)
	s_barrier
; #define PG8_STAGE(bufoff, gbase, voff) do { _Pragma("unroll") for (int _i = 0; _i < 2; ++_i) \
;         __builtin_amdgcn_global_load_lds((const unsigned*)((const char*)(gbase) + (voff)[_i]), (LAS unsigned*)(lds + (bufoff) + ldsw + _i * 8192), 16, 0, 0); } while (0)
; #define PG8_LDA(dst, b, h) do { _Pragma("unroll") for (int m = 0; m < 4; ++m) _Pragma("unroll") for (int k = 0; k < 2; ++k) dst[m][k] = *(const LAS bf16x8*)(lds + PG8_SA(b, h) + aoff + m * 2048 + k * 1024); } while (0)
; #define PG8_LDB(dst, b, h) do { _Pragma("unroll") for (int n = 0; n < 2; ++n) _Pragma("unroll") for (int k = 0; k < 2; ++k) dst[n][k] = *(const LAS bf16x8*)(lds + PG8_SB(b, h) + boff + n * 2048 + k * 1024); } while (0)
; #define PG8_MMA(ai, bj, At, Bt) do { __builtin_amdgcn_s_setprio(1); _Pragma("unroll") for (int m = 0; m < 4; ++m) _Pragma("unroll") for (int n = 0; n < 2; ++n) _Pragma("unroll") for (int k = 0; k < 2; ++k) \
;         acc[ai][bj][m][n] = __builtin_amdgcn_mfma_f32_16x16x32_bf16(Bt[n][k], At[m][k], acc[ai][bj][m][n], 0, 0, 0); __builtin_amdgcn_s_setprio(0); } while (0)
; #define PG8_WAIT_V(n) asm volatile("s_waitcnt vmcnt(" #n ")" ::: "memory")
; #define PG8_WAIT_L(n) asm volatile("s_waitcnt lgkmcnt(" #n ")" ::: "memory")
; #define PG8_BAR __builtin_amdgcn_s_barrier()
; #define PG8_SCHED __builtin_amdgcn_sched_barrier(0)
; template <class Epi, class Sched, int LD>
; __device__ __forceinline__ void gemm_phase(LAS unsigned char* lds, const Gemm g, const Sched& S, const Epi& E) {
;     ...
;             PG8_WAIT_V(6); PG8_BAR; PG8_MMA(1, 1, At, B1); PG8_BAR;
;             PG8_LDB(B0, 1, 0); PG8_SCHED; PG8_LDA(At, 1, 0); PG8_STAGE(PG8_SA(0, 1), a2 + hstep, voffA);
;             PG8_WAIT_L(8); PG8_BAR; PG8_WAIT_L(0); PG8_MMA(0, 0, At, B0); PG8_BAR; PG8_SCHED;
;             PG8_LDB(B1, 1, 1); PG8_STAGE(PG8_SB(1, 0), b3, voffB);
;             PG8_BAR; PG8_WAIT_L(0); PG8_MMA(0, 1, At, B1); PG8_BAR;
;             PG8_LDA(At, 1, 1); PG8_STAGE(PG8_SA(1, 0), a3, voffA);
	s_setprio 1
	v_mfma_f32_16x16x32_bf16 v[56:59], v[212:215], v[180:183], v[56:59]
	v_mfma_f32_16x16x32_bf16 v[52:55], v[220:223], v[180:183], v[52:55]
	v_mfma_f32_16x16x32_bf16 v[40:43], v[212:215], v[188:191], v[40:43]
	v_mfma_f32_16x16x32_bf16 v[36:39], v[220:223], v[188:191], v[36:39]
	v_mfma_f32_16x16x32_bf16 v[24:27], v[212:215], v[196:199], v[24:27]
	v_mfma_f32_16x16x32_bf16 v[20:23], v[220:223], v[196:199], v[20:23]
	v_mfma_f32_16x16x32_bf16 v[8:11], v[212:215], v[204:207], v[8:11]
	v_mfma_f32_16x16x32_bf16 v[4:7], v[220:223], v[204:207], v[4:7]
	v_mfma_f32_16x16x32_bf16 v[56:59], v[216:219], v[184:187], v[56:59]
	v_mfma_f32_16x16x32_bf16 v[52:55], v[224:227], v[184:187], v[52:55]
	v_mfma_f32_16x16x32_bf16 v[40:43], v[216:219], v[192:195], v[40:43]
	v_mfma_f32_16x16x32_bf16 v[36:39], v[224:227], v[192:195], v[36:39]
	v_mfma_f32_16x16x32_bf16 v[24:27], v[216:219], v[200:203], v[24:27]
	v_mfma_f32_16x16x32_bf16 v[20:23], v[224:227], v[200:203], v[20:23]
	v_mfma_f32_16x16x32_bf16 v[8:11], v[216:219], v[208:211], v[8:11]
	v_mfma_f32_16x16x32_bf16 v[4:7], v[224:227], v[208:211], v[4:7]
	s_setprio 0
	s_add_i32 s72, 0, 0x18000
	s_barrier
	ds_read_b128 v[140:143], v228 offset:32768
	ds_read_b128 v[150:153], v228 offset:33792
	ds_read_b128 v[154:157], v228 offset:34816
	ds_read_b128 v[176:179], v228 offset:35840
	s_add_u32 s4, s4, 0x4000
	s_addc_u32 s5, s5, 0
	s_mov_b32 m0, s53
	ds_read_b128 v[180:183], v148 offset:32768
	ds_read_b128 v[184:187], v148 offset:33792
	ds_read_b128 v[188:191], v148 offset:34816
	ds_read_b128 v[192:195], v148 offset:35840
	ds_read_b128 v[196:199], v148 offset:36864
	ds_read_b128 v[200:203], v148 offset:37888
	ds_read_b128 v[204:207], v148 offset:38912
	ds_read_b128 v[208:211], v148 offset:39936
	global_load_lds_dwordx4 v132, s[4:5]
	s_mov_b32 m0, s54
	s_nop 0
	global_load_lds_dwordx4 v138, s[4:5]
	s_waitcnt lgkmcnt(8)
	s_barrier
	s_waitcnt lgkmcnt(0)
	s_setprio 1
	v_mfma_f32_16x16x32_bf16 v[128:131], v[140:143], v[180:183], v[128:131]
	v_mfma_f32_16x16x32_bf16 v[124:127], v[154:157], v[180:183], v[124:127]
	v_mfma_f32_16x16x32_bf16 v[112:115], v[140:143], v[188:191], v[112:115]
	v_mfma_f32_16x16x32_bf16 v[108:111], v[154:157], v[188:191], v[108:111]
	v_mfma_f32_16x16x32_bf16 v[96:99], v[140:143], v[196:199], v[96:99]
	v_mfma_f32_16x16x32_bf16 v[92:95], v[154:157], v[196:199], v[92:95]
	v_mfma_f32_16x16x32_bf16 v[80:83], v[140:143], v[204:207], v[80:83]
	v_mfma_f32_16x16x32_bf16 v[76:79], v[154:157], v[204:207], v[76:79]
	v_mfma_f32_16x16x32_bf16 v[128:131], v[150:153], v[184:187], v[128:131]
	v_mfma_f32_16x16x32_bf16 v[124:127], v[176:179], v[184:187], v[124:127]
	v_mfma_f32_16x16x32_bf16 v[112:115], v[150:153], v[192:195], v[112:115]
	v_mfma_f32_16x16x32_bf16 v[108:111], v[176:179], v[192:195], v[108:111]
	v_mfma_f32_16x16x32_bf16 v[96:99], v[150:153], v[200:203], v[96:99]
	v_mfma_f32_16x16x32_bf16 v[92:95], v[176:179], v[200:203], v[92:95]
	s_setprio 2
	s_barrier
	v_mfma_f32_16x16x32_bf16 v[80:83], v[150:153], v[208:211], v[80:83]
	v_mfma_f32_16x16x32_bf16 v[76:79], v[176:179], v[208:211], v[76:79]
	s_setprio 0
	s_add_i32 s73, 0, 0x1c000
	s_add_u32 s4, s48, 0x8000
	s_addc_u32 s5, s49, 0
	s_add_i32 s72, s72, s29
	ds_read_b128 v[212:215], v228 offset:49152
	ds_read_b128 v[216:219], v228 offset:50176
	ds_read_b128 v[220:223], v228 offset:51200
	ds_read_b128 v[224:227], v228 offset:52224
	s_mov_b32 m0, s72
	s_nop 0
	global_load_lds_dwordx4 v132, s[4:5]
	s_add_i32 m0, s72, 0x2000
	s_nop 0
	global_load_lds_dwordx4 v138, s[4:5]
	s_barrier
	s_waitcnt lgkmcnt(0)
	s_setprio 1
	v_mfma_f32_16x16x32_bf16 v[120:123], v[212:215], v[180:183], v[120:123]
	v_mfma_f32_16x16x32_bf16 v[116:119], v[220:223], v[180:183], v[116:119]
	v_mfma_f32_16x16x32_bf16 v[104:107], v[212:215], v[188:191], v[104:107]
	v_mfma_f32_16x16x32_bf16 v[100:103], v[220:223], v[188:191], v[100:103]
	v_mfma_f32_16x16x32_bf16 v[88:91], v[212:215], v[196:199], v[88:91]
	v_mfma_f32_16x16x32_bf16 v[84:87], v[220:223], v[196:199], v[84:87]
	v_mfma_f32_16x16x32_bf16 v[72:75], v[212:215], v[204:207], v[72:75]
	v_mfma_f32_16x16x32_bf16 v[68:71], v[220:223], v[204:207], v[68:71]
	v_mfma_f32_16x16x32_bf16 v[120:123], v[216:219], v[184:187], v[120:123]
	v_mfma_f32_16x16x32_bf16 v[116:119], v[224:227], v[184:187], v[116:119]
	v_mfma_f32_16x16x32_bf16 v[104:107], v[216:219], v[192:195], v[104:107]
	v_mfma_f32_16x16x32_bf16 v[100:103], v[224:227], v[192:195], v[100:103]
	v_mfma_f32_16x16x32_bf16 v[88:91], v[216:219], v[200:203], v[88:91]
	v_mfma_f32_16x16x32_bf16 v[84:87], v[224:227], v[200:203], v[84:87]
	v_mfma_f32_16x16x32_bf16 v[72:75], v[216:219], v[208:211], v[72:75]
	v_mfma_f32_16x16x32_bf16 v[68:71], v[224:227], v[208:211], v[68:71]
	s_setprio 0
	s_mov_b32 m0, s55
	s_barrier
	ds_read_b128 v[180:183], v148 offset:49152
	ds_read_b128 v[184:187], v148 offset:50176
	ds_read_b128 v[188:191], v148 offset:51200
	ds_read_b128 v[192:195], v148 offset:52224
	ds_read_b128 v[196:199], v148 offset:53248
	ds_read_b128 v[200:203], v148 offset:54272
	ds_read_b128 v[204:207], v148 offset:55296
	ds_read_b128 v[208:211], v148 offset:56320
	global_load_lds_dwordx4 v132, s[50:51]
	s_mov_b32 m0, s56
	s_nop 0
	global_load_lds_dwordx4 v138, s[50:51]
	s_barrier
; #define PG8_STAGE(bufoff, gbase, voff) do { _Pragma("unroll") for (int _i = 0; _i < 2; ++_i) \
;         __builtin_amdgcn_global_load_lds((const unsigned*)((const char*)(gbase) + (voff)[_i]), (LAS unsigned*)(lds + (bufoff) + ldsw + _i * 8192), 16, 0, 0); } while (0)
; #define PG8_MMA(ai, bj, At, Bt) do { __builtin_amdgcn_s_setprio(1); _Pragma("unroll") for (int m = 0; m < 4; ++m) _Pragma("unroll") for (int n = 0; n < 2; ++n) _Pragma("unroll") for (int k = 0; k < 2; ++k) \
;         acc[ai][bj][m][n] = __builtin_amdgcn_mfma_f32_16x16x32_bf16(Bt[n][k], At[m][k], acc[ai][bj][m][n], 0, 0, 0); __builtin_amdgcn_s_setprio(0); } while (0)
; #define PG8_WAIT_V(n) asm volatile("s_waitcnt vmcnt(" #n ")" ::: "memory")
; #define PG8_WAIT_L(n) asm volatile("s_waitcnt lgkmcnt(" #n ")" ::: "memory")
; #define PG8_BAR __builtin_amdgcn_s_barrier()
; #define PG8_SCHED __builtin_amdgcn_sched_barrier(0)
;     __device__ __forceinline__ void operator()(const f32x4 (&acc)[2][2][4][2], const Unit& u, int wr, int wc, int fr, int fq) const {
;     ...
;         } else {
;             float* base = PART + (size_t)u.part * (512 * 2048);
; #pragma unroll
;             for (int ai = 0; ai < 2; ++ai)
; #pragma unroll
;                 for (int m = 0; m < 4; ++m) {
;                     float* rowp = base + (size_t)(row0 - 8192 + ai * HALF + m * 16) * D_MODEL + col0;
; #pragma unroll
;                     for (int bj = 0; bj < 2; ++bj)
; #pragma unroll
;                         for (int n = 0; n < 2; ++n) *(f32x4*)(rowp + bj * HALF + n * 16) = acc[ai][bj][m][n];
;                 }
; template <class Epi, class Sched, int LD>
; __device__ __forceinline__ void gemm_phase(LAS unsigned char* lds, const Gemm g, const Sched& S, const Epi& E) {
;     ...
;             PG8_BAR; PG8_WAIT_L(0); PG8_MMA(1, 0, At, B0); PG8_BAR; PG8_SCHED;
;             PG8_STAGE(PG8_SB(1, 1), b3 + hstep, voffB);
;             PG8_WAIT_V(6); PG8_BAR; PG8_MMA(1, 1, At, B1); PG8_BAR;
;         }
	s_waitcnt lgkmcnt(0)
	s_setprio 1
	v_mfma_f32_16x16x32_bf16 v[64:67], v[140:143], v[180:183], v[64:67]
	v_mfma_f32_16x16x32_bf16 v[60:63], v[154:157], v[180:183], v[60:63]
	v_mfma_f32_16x16x32_bf16 v[48:51], v[140:143], v[188:191], v[48:51]
	v_mfma_f32_16x16x32_bf16 v[44:47], v[154:157], v[188:191], v[44:47]
	v_mfma_f32_16x16x32_bf16 v[32:35], v[140:143], v[196:199], v[32:35]
	v_mfma_f32_16x16x32_bf16 v[28:31], v[154:157], v[196:199], v[28:31]
	v_mfma_f32_16x16x32_bf16 v[16:19], v[140:143], v[204:207], v[16:19]
	v_mfma_f32_16x16x32_bf16 v[12:15], v[154:157], v[204:207], v[12:15]
	v_mfma_f32_16x16x32_bf16 v[64:67], v[150:153], v[184:187], v[64:67]
	v_mfma_f32_16x16x32_bf16 v[60:63], v[176:179], v[184:187], v[60:63]
	v_mfma_f32_16x16x32_bf16 v[48:51], v[150:153], v[192:195], v[48:51]
	v_mfma_f32_16x16x32_bf16 v[44:47], v[176:179], v[192:195], v[44:47]
	v_mfma_f32_16x16x32_bf16 v[32:35], v[150:153], v[200:203], v[32:35]
	v_mfma_f32_16x16x32_bf16 v[28:31], v[176:179], v[200:203], v[28:31]
	s_setprio 2
	s_barrier
	v_mfma_f32_16x16x32_bf16 v[16:19], v[150:153], v[208:211], v[16:19]
	v_mfma_f32_16x16x32_bf16 v[12:15], v[176:179], v[208:211], v[12:15]
	s_setprio 0
	s_add_u32 s4, s48, 0xc000
	s_addc_u32 s5, s49, 0
	s_add_i32 s48, s73, s29
	s_mov_b32 m0, s48
	s_nop 0
	global_load_lds_dwordx4 v132, s[4:5]
	s_add_i32 m0, s48, 0x2000
	s_nop 0
	global_load_lds_dwordx4 v138, s[4:5]
	s_waitcnt vmcnt(6)
	s_barrier
	s_setprio 1
	v_mfma_f32_16x16x32_bf16 v[56:59], v[212:215], v[180:183], v[56:59]
	v_mfma_f32_16x16x32_bf16 v[52:55], v[220:223], v[180:183], v[52:55]
	v_mfma_f32_16x16x32_bf16 v[40:43], v[212:215], v[188:191], v[40:43]
	v_mfma_f32_16x16x32_bf16 v[36:39], v[220:223], v[188:191], v[36:39]
	v_mfma_f32_16x16x32_bf16 v[24:27], v[212:215], v[196:199], v[24:27]
	v_mfma_f32_16x16x32_bf16 v[20:23], v[220:223], v[196:199], v[20:23]
	v_mfma_f32_16x16x32_bf16 v[8:11], v[212:215], v[204:207], v[8:11]
	v_mfma_f32_16x16x32_bf16 v[4:7], v[220:223], v[204:207], v[4:7]
	v_mfma_f32_16x16x32_bf16 v[56:59], v[216:219], v[184:187], v[56:59]
	v_mfma_f32_16x16x32_bf16 v[52:55], v[224:227], v[184:187], v[52:55]
	v_mfma_f32_16x16x32_bf16 v[40:43], v[216:219], v[192:195], v[40:43]
	v_mfma_f32_16x16x32_bf16 v[36:39], v[224:227], v[192:195], v[36:39]
	v_mfma_f32_16x16x32_bf16 v[24:27], v[216:219], v[200:203], v[24:27]
	v_mfma_f32_16x16x32_bf16 v[20:23], v[224:227], v[200:203], v[20:23]
	v_mfma_f32_16x16x32_bf16 v[8:11], v[216:219], v[208:211], v[8:11]
	v_mfma_f32_16x16x32_bf16 v[4:7], v[224:227], v[208:211], v[4:7]
	s_setprio 0
	s_add_u32 s46, s46, 0x10000
	s_addc_u32 s47, s47, 0
	s_add_u32 s69, s69, 0x10000
	s_addc_u32 s70, s70, 0
	s_cmp_ge_i32 s71, s65
	s_mov_b32 s4, s71
	s_barrier
	s_cbranch_scc0 .LBB0_58
	v_lshl_add_u32 v142, s67, 8, v137
	v_lshl_or_b32 v140, s66, 8, v147
	s_mov_b64 s[4:5], -1
	s_cmp_gt_i32 s18, -1
	v_ashrrev_i32_e32 v141, 31, v140
	v_ashrrev_i32_e32 v143, 31, v142
	s_cbranch_scc0 .LBB0_61
	s_lshl_b64 s[4:5], s[18:19], 22
	v_readlane_b32 s18, v252, 10
	s_add_u32 s4, s18, s4
	v_readlane_b32 s18, v252, 11
	s_addc_u32 s5, s18, s5
	v_lshl_add_u64 v[144:145], v[140:141], 2, s[4:5]
	v_lshlrev_b64 v[150:151], 13, v[142:143]
	s_brev_b32 s4, 63
	v_lshl_add_u64 v[144:145], v[144:145], 0, v[150:151]
	s_mov_b32 s5, -1
	v_lshl_add_u64 v[150:151], v[144:145], 0, s[4:5]
	s_brev_b32 s4, 63
	v_add_co_u32_e32 v152, vcc, s4, v144
	s_mov_b32 s4, 0xfc020000
	s_nop 0
	v_addc_co_u32_e32 v153, vcc, -1, v145, vcc
	s_mov_b32 s5, -1
	global_store_dwordx4 v[152:153], v[128:131], off
	global_store_dwordx4 v[150:151], v[124:127], off offset:64
	global_store_dwordx4 v[150:151], v[120:123], off offset:512
	global_store_dwordx4 v[150:151], v[116:119], off offset:576
	v_lshl_add_u64 v[150:151], v[144:145], 0, s[4:5]
	s_mov_b32 s4, 0xfc020000
	v_add_co_u32_e32 v152, vcc, s4, v144
	s_mov_b32 s4, 0xfc040000
	s_nop 0
	v_addc_co_u32_e32 v153, vcc, -1, v145, vcc
	s_mov_b32 s5, -1
	global_store_dwordx4 v[152:153], v[112:115], off
	global_store_dwordx4 v[150:151], v[108:111], off offset:64
	global_store_dwordx4 v[150:151], v[104:107], off offset:512
	global_store_dwordx4 v[150:151], v[100:103], off offset:576
	v_lshl_add_u64 v[150:151], v[144:145], 0, s[4:5]
	s_mov_b32 s4, 0xfc040000
	v_add_co_u32_e32 v152, vcc, s4, v144
	s_mov_b32 s4, 0xfc060000
	s_nop 0
	v_addc_co_u32_e32 v153, vcc, -1, v145, vcc
	s_mov_b32 s5, -1
	global_store_dwordx4 v[152:153], v[96:99], off
	global_store_dwordx4 v[150:151], v[92:95], off offset:64
	global_store_dwordx4 v[150:151], v[88:91], off offset:512
	global_store_dwordx4 v[150:151], v[84:87], off offset:576
	v_lshl_add_u64 v[150:151], v[144:145], 0, s[4:5]
	s_mov_b32 s4, 0xfc060000
	v_add_co_u32_e32 v152, vcc, s4, v144
	s_mov_b32 s4, 0xfc100000
	s_nop 0
	v_addc_co_u32_e32 v153, vcc, -1, v145, vcc
	s_mov_b32 s5, -1
	global_store_dwordx4 v[152:153], v[80:83], off
	global_store_dwordx4 v[150:151], v[76:79], off offset:64
	global_store_dwordx4 v[150:151], v[72:75], off offset:512
	global_store_dwordx4 v[150:151], v[68:71], off offset:576
	v_lshl_add_u64 v[150:151], v[144:145], 0, s[4:5]
	s_mov_b32 s4, 0xfc100000
	v_add_co_u32_e32 v152, vcc, s4, v144
	s_mov_b32 s4, 0xfc120000
	s_nop 0
	v_addc_co_u32_e32 v153, vcc, -1, v145, vcc
	s_mov_b32 s5, -1
	global_store_dwordx4 v[152:153], v[64:67], off
	global_store_dwordx4 v[150:151], v[60:63], off offset:64
	global_store_dwordx4 v[150:151], v[56:59], off offset:512
	global_store_dwordx4 v[150:151], v[52:55], off offset:576
	v_lshl_add_u64 v[150:151], v[144:145], 0, s[4:5]
	s_mov_b32 s4, 0xfc120000
	v_add_co_u32_e32 v152, vcc, s4, v144
	s_mov_b32 s4, 0xfc140000
	s_nop 0
	v_addc_co_u32_e32 v153, vcc, -1, v145, vcc
	s_mov_b32 s5, -1
	global_store_dwordx4 v[152:153], v[48:51], off
	global_store_dwordx4 v[150:151], v[44:47], off offset:64
	global_store_dwordx4 v[150:151], v[40:43], off offset:512
	global_store_dwordx4 v[150:151], v[36:39], off offset:576
	v_lshl_add_u64 v[150:151], v[144:145], 0, s[4:5]
	s_mov_b32 s4, 0xfc140000
	v_add_co_u32_e32 v152, vcc, s4, v144
	s_mov_b32 s4, 0xfc160000
	s_nop 0
	v_addc_co_u32_e32 v153, vcc, -1, v145, vcc
	s_mov_b32 s5, -1
	global_store_dwordx4 v[152:153], v[32:35], off
	global_store_dwordx4 v[150:151], v[28:31], off offset:64
	global_store_dwordx4 v[150:151], v[24:27], off offset:512
	global_store_dwordx4 v[150:151], v[20:23], off offset:576
	v_lshl_add_u64 v[150:151], v[144:145], 0, s[4:5]
	v_add_co_u32_e32 v144, vcc, 0xfc160000, v144
	s_mov_b64 s[4:5], 0
	s_nop 0
	v_addc_co_u32_e32 v145, vcc, -1, v145, vcc
	global_store_dwordx4 v[144:145], v[16:19], off
	global_store_dwordx4 v[150:151], v[12:15], off offset:64
	global_store_dwordx4 v[150:151], v[8:11], off offset:512
	global_store_dwordx4 v[150:151], v[4:7], off offset:576

; #define PG8_STAGE(bufoff, gbase, voff) do { _Pragma("unroll") for (int _i = 0; _i < 2; ++_i) \
;         __builtin_amdgcn_global_load_lds((const unsigned*)((const char*)(gbase) + (voff)[_i]), (LAS unsigned*)(lds + (bufoff) + ldsw + _i * 8192), 16, 0, 0); } while (0)
; #define PG8_LDA(dst, b, h) do { _Pragma("unroll") for (int m = 0; m < 4; ++m) _Pragma("unroll") for (int k = 0; k < 2; ++k) dst[m][k] = *(const LAS bf16x8*)(lds + PG8_SA(b, h) + aoff + m * 2048 + k * 1024); } while (0)
; #define PG8_LDB(dst, b, h) do { _Pragma("unroll") for (int n = 0; n < 2; ++n) _Pragma("unroll") for (int k = 0; k < 2; ++k) dst[n][k] = *(const LAS bf16x8*)(lds + PG8_SB(b, h) + boff + n * 2048 + k * 1024); } while (0)
; #define PG8_MMA(ai, bj, At, Bt) do { __builtin_amdgcn_s_setprio(1); _Pragma("unroll") for (int m = 0; m < 4; ++m) _Pragma("unroll") for (int n = 0; n < 2; ++n) _Pragma("unroll") for (int k = 0; k < 2; ++k) \
;         acc[ai][bj][m][n] = __builtin_amdgcn_mfma_f32_16x16x32_bf16(Bt[n][k], At[m][k], acc[ai][bj][m][n], 0, 0, 0); __builtin_amdgcn_s_setprio(0); } while (0)
; #define PG8_WAIT_L(n) asm volatile("s_waitcnt lgkmcnt(" #n ")" ::: "memory")
; #define PG8_BAR __builtin_amdgcn_s_barrier()
; #define PG8_SCHED __builtin_amdgcn_sched_barrier(0)
; template <class Epi, class Sched, int LD>
; __device__ __forceinline__ void gemm_phase(LAS unsigned char* lds, const Gemm g, const Sched& S, const Epi& E) {
;     ...
;         for (int t = 0; t < nt; t += 2) {
;             const bool last = (t == nt - 2);
;             const char* a1 = cA + (size_t)(t + 1) * kstep;
;             const char* a2 = last ? nA : cA + (size_t)(t + 2) * kstep; const char* b2 = last ? nB : cB + (size_t)(t + 2) * kstep;
;             const char* a3 = a2 + kstep; const char* b3 = b2 + kstep;
;             PG8_LDB(B0, 0, 0); PG8_SCHED; PG8_LDA(At, 0, 0); PG8_STAGE(PG8_SA(1, 1), a1 + hstep, voffA);
;             PG8_WAIT_L(8); PG8_BAR; PG8_WAIT_L(0); PG8_MMA(0, 0, At, B0); PG8_BAR; PG8_SCHED;
;             PG8_LDB(B1, 0, 1); PG8_STAGE(PG8_SB(0, 0), b2, voffB);
;             PG8_BAR; PG8_WAIT_L(0); PG8_MMA(0, 1, At, B1); PG8_BAR;
;             PG8_LDA(At, 0, 1); PG8_STAGE(PG8_SA(0, 0), a2, voffA);
;             PG8_BAR; PG8_WAIT_L(0); PG8_MMA(1, 0, At, B0); PG8_BAR; PG8_SCHED;
;             PG8_STAGE(PG8_SB(0, 1), b2 + hstep, voffB);
.LBB0_501:
	s_add_u32 s4, s54, 0x4000
	s_addc_u32 s5, s55, 0
	s_cmp_eq_u32 s49, 28
	s_cselect_b32 s4, s50, s4
	s_cselect_b32 s5, s51, s5
	s_cselect_b32 s56, s40, s29
	s_cselect_b32 s57, s41, s47
	s_add_u32 s58, s4, 0x8000
	s_addc_u32 s59, s5, 0
	s_add_i32 s69, 0, 0x10000
	ds_read_b128 v[148:151], v228
	ds_read_b128 v[152:155], v228 offset:1024
	ds_read_b128 v[156:159], v228 offset:2048
	ds_read_b128 v[176:179], v228 offset:3072
	s_add_i32 m0, s52, 0xc000
	ds_read_b128 v[180:183], v146
	ds_read_b128 v[184:187], v146 offset:1024
	ds_read_b128 v[188:191], v146 offset:2048
	ds_read_b128 v[192:195], v146 offset:3072
	ds_read_b128 v[196:199], v146 offset:4096
	ds_read_b128 v[200:203], v146 offset:5120
	ds_read_b128 v[204:207], v146 offset:6144
	ds_read_b128 v[208:211], v146 offset:7168
	global_load_lds_dwordx4 v132, s[54:55]
	s_add_i32 m0, s52, 0xe000
	s_nop 0
	global_load_lds_dwordx4 v138, s[54:55]
	s_waitcnt lgkmcnt(8)
	s_barrier
	s_waitcnt lgkmcnt(0)
	s_setprio 1
	v_mfma_f32_16x16x32_bf16 v[128:131], v[148:151], v[180:183], v[128:131]
	v_mfma_f32_16x16x32_bf16 v[124:127], v[156:159], v[180:183], v[124:127]
	v_mfma_f32_16x16x32_bf16 v[120:123], v[148:151], v[188:191], v[120:123]
	v_mfma_f32_16x16x32_bf16 v[116:119], v[156:159], v[188:191], v[116:119]
	v_mfma_f32_16x16x32_bf16 v[104:107], v[148:151], v[196:199], v[104:107]
	v_mfma_f32_16x16x32_bf16 v[100:103], v[156:159], v[196:199], v[100:103]
	v_mfma_f32_16x16x32_bf16 v[88:91], v[148:151], v[204:207], v[88:91]
	v_mfma_f32_16x16x32_bf16 v[84:87], v[156:159], v[204:207], v[84:87]
	v_mfma_f32_16x16x32_bf16 v[128:131], v[152:155], v[184:187], v[128:131]
	v_mfma_f32_16x16x32_bf16 v[124:127], v[176:179], v[184:187], v[124:127]
	v_mfma_f32_16x16x32_bf16 v[120:123], v[152:155], v[192:195], v[120:123]
	v_mfma_f32_16x16x32_bf16 v[116:119], v[176:179], v[192:195], v[116:119]
	v_mfma_f32_16x16x32_bf16 v[104:107], v[152:155], v[200:203], v[104:107]
	v_mfma_f32_16x16x32_bf16 v[100:103], v[176:179], v[200:203], v[100:103]
	s_setprio 2
	s_barrier
	v_mfma_f32_16x16x32_bf16 v[88:91], v[152:155], v[208:211], v[88:91]
	v_mfma_f32_16x16x32_bf16 v[84:87], v[176:179], v[208:211], v[84:87]
	s_setprio 0
	s_add_i32 s72, 0, 0x14000
	s_add_i32 s69, s69, s39
	ds_read_b128 v[212:215], v228 offset:16384
	ds_read_b128 v[216:219], v228 offset:17408
	ds_read_b128 v[220:223], v228 offset:18432
	ds_read_b128 v[224:227], v228 offset:19456
	s_mov_b32 m0, s69
	s_nop 0
	global_load_lds_dwordx4 v132, s[56:57]
	s_add_i32 m0, s69, 0x2000
	s_nop 0
	global_load_lds_dwordx4 v138, s[56:57]
	s_barrier
	s_waitcnt lgkmcnt(0)
	s_setprio 1
	v_mfma_f32_16x16x32_bf16 v[112:115], v[212:215], v[180:183], v[112:115]
	v_mfma_f32_16x16x32_bf16 v[108:111], v[220:223], v[180:183], v[108:111]
	v_mfma_f32_16x16x32_bf16 v[96:99], v[212:215], v[188:191], v[96:99]
	v_mfma_f32_16x16x32_bf16 v[92:95], v[220:223], v[188:191], v[92:95]
	v_mfma_f32_16x16x32_bf16 v[80:83], v[212:215], v[196:199], v[80:83]
	v_mfma_f32_16x16x32_bf16 v[76:79], v[220:223], v[196:199], v[76:79]
	v_mfma_f32_16x16x32_bf16 v[72:75], v[212:215], v[204:207], v[72:75]
	v_mfma_f32_16x16x32_bf16 v[68:71], v[220:223], v[204:207], v[68:71]
	v_mfma_f32_16x16x32_bf16 v[112:115], v[216:219], v[184:187], v[112:115]
	v_mfma_f32_16x16x32_bf16 v[108:111], v[224:227], v[184:187], v[108:111]
	v_mfma_f32_16x16x32_bf16 v[96:99], v[216:219], v[192:195], v[96:99]
	v_mfma_f32_16x16x32_bf16 v[92:95], v[224:227], v[192:195], v[92:95]
	v_mfma_f32_16x16x32_bf16 v[80:83], v[216:219], v[200:203], v[80:83]
	v_mfma_f32_16x16x32_bf16 v[76:79], v[224:227], v[200:203], v[76:79]
	v_mfma_f32_16x16x32_bf16 v[72:75], v[216:219], v[208:211], v[72:75]
	v_mfma_f32_16x16x32_bf16 v[68:71], v[224:227], v[208:211], v[68:71]
	s_setprio 0
	s_mov_b32 m0, s52
	s_barrier
	ds_read_b128 v[180:183], v146 offset:16384
	ds_read_b128 v[184:187], v146 offset:17408
	ds_read_b128 v[188:191], v146 offset:18432
	ds_read_b128 v[192:195], v146 offset:19456
	ds_read_b128 v[196:199], v146 offset:20480
	ds_read_b128 v[200:203], v146 offset:21504
	ds_read_b128 v[204:207], v146 offset:22528
	ds_read_b128 v[208:211], v146 offset:23552
	global_load_lds_dwordx4 v132, s[4:5]
	s_mov_b32 m0, s53
	s_nop 0
	global_load_lds_dwordx4 v138, s[4:5]
	s_barrier
	s_waitcnt lgkmcnt(0)
	s_setprio 1
	v_mfma_f32_16x16x32_bf16 v[64:67], v[148:151], v[180:183], v[64:67]
	v_mfma_f32_16x16x32_bf16 v[60:63], v[156:159], v[180:183], v[60:63]
	v_mfma_f32_16x16x32_bf16 v[56:59], v[148:151], v[188:191], v[56:59]
	v_mfma_f32_16x16x32_bf16 v[52:55], v[156:159], v[188:191], v[52:55]
	v_mfma_f32_16x16x32_bf16 v[40:43], v[148:151], v[196:199], v[40:43]
	v_mfma_f32_16x16x32_bf16 v[36:39], v[156:159], v[196:199], v[36:39]
	v_mfma_f32_16x16x32_bf16 v[24:27], v[148:151], v[204:207], v[24:27]
	v_mfma_f32_16x16x32_bf16 v[20:23], v[156:159], v[204:207], v[20:23]
	v_mfma_f32_16x16x32_bf16 v[64:67], v[152:155], v[184:187], v[64:67]
	v_mfma_f32_16x16x32_bf16 v[60:63], v[176:179], v[184:187], v[60:63]
	v_mfma_f32_16x16x32_bf16 v[56:59], v[152:155], v[192:195], v[56:59]
	v_mfma_f32_16x16x32_bf16 v[52:55], v[176:179], v[192:195], v[52:55]
	v_mfma_f32_16x16x32_bf16 v[40:43], v[152:155], v[200:203], v[40:43]
	v_mfma_f32_16x16x32_bf16 v[36:39], v[176:179], v[200:203], v[36:39]
	s_setprio 2
	s_barrier
	v_mfma_f32_16x16x32_bf16 v[24:27], v[152:155], v[208:211], v[24:27]
	v_mfma_f32_16x16x32_bf16 v[20:23], v[176:179], v[208:211], v[20:23]
	s_setprio 0
	s_add_u32 s70, s56, 0x4000
	s_addc_u32 s71, s57, 0
	s_add_i32 s69, s72, s39
	s_mov_b32 m0, s69
	s_nop 0
	global_load_lds_dwordx4 v132, s[70:71]
	s_add_i32 m0, s69, 0x2000
	s_nop 0
	global_load_lds_dwordx4 v138, s[70:71]
	s_waitcnt vmcnt(6)
	s_barrier
; #define PG8_STAGE(bufoff, gbase, voff) do { _Pragma("unroll") for (int _i = 0; _i < 2; ++_i) \
;         __builtin_amdgcn_global_load_lds((const unsigned*)((const char*)(gbase) + (voff)[_i]), (LAS unsigned*)(lds + (bufoff) + ldsw + _i * 8192), 16, 0, 0); } while (0)
; #define PG8_LDA(dst, b, h) do { _Pragma("unroll") for (int m = 0; m < 4; ++m) _Pragma("unroll") for (int k = 0; k < 2; ++k) dst[m][k] = *(const LAS bf16x8*)(lds + PG8_SA(b, h) + aoff + m * 2048 + k * 1024); } while (0)
; #define PG8_LDB(dst, b, h) do { _Pragma("unroll") for (int n = 0; n < 2; ++n) _Pragma("unroll") for (int k = 0; k < 2; ++k) dst[n][k] = *(const LAS bf16x8*)(lds + PG8_SB(b, h) + boff + n * 2048 + k * 1024); } while (0)
; #define PG8_MMA(ai, bj, At, Bt) do { __builtin_amdgcn_s_setprio(1); _Pragma("unroll") for (int m = 0; m < 4; ++m) _Pragma("unroll") for (int n = 0; n < 2; ++n) _Pragma("unroll") for (int k = 0; k < 2; ++k) \
;         acc[ai][bj][m][n] = __builtin_amdgcn_mfma_f32_16x16x32_bf16(Bt[n][k], At[m][k], acc[ai][bj][m][n], 0, 0, 0); __builtin_amdgcn_s_setprio(0); } while (0)
; #define PG8_WAIT_V(n) asm volatile("s_waitcnt vmcnt(" #n ")" ::: "memory")
; #define PG8_WAIT_L(n) asm volatile("s_waitcnt lgkmcnt(" #n ")" ::: "memory")
; #define PG8_BAR __builtin_amdgcn_s_barrier()
; #define PG8_SCHED __builtin_amdgcn_sched_barrier(0)
; template <class Epi, class Sched, int LD>
; __device__ __forceinline__ void gemm_phase(LAS unsigned char* lds, const Gemm g, const Sched& S, const Epi& E) {
;     ...
;             PG8_WAIT_V(6); PG8_BAR; PG8_MMA(1, 1, At, B1); PG8_BAR;
;             PG8_LDB(B0, 1, 0); PG8_SCHED; PG8_LDA(At, 1, 0); PG8_STAGE(PG8_SA(0, 1), a2 + hstep, voffA);
;             PG8_WAIT_L(8); PG8_BAR; PG8_WAIT_L(0); PG8_MMA(0, 0, At, B0); PG8_BAR; PG8_SCHED;
;             PG8_LDB(B1, 1, 1); PG8_STAGE(PG8_SB(1, 0), b3, voffB);
;             PG8_BAR; PG8_WAIT_L(0); PG8_MMA(0, 1, At, B1); PG8_BAR;
;             PG8_LDA(At, 1, 1); PG8_STAGE(PG8_SA(1, 0), a3, voffA);
	s_setprio 1
	v_mfma_f32_16x16x32_bf16 v[48:51], v[212:215], v[180:183], v[48:51]
	v_mfma_f32_16x16x32_bf16 v[44:47], v[220:223], v[180:183], v[44:47]
	v_mfma_f32_16x16x32_bf16 v[32:35], v[212:215], v[188:191], v[32:35]
	v_mfma_f32_16x16x32_bf16 v[28:31], v[220:223], v[188:191], v[28:31]
	v_mfma_f32_16x16x32_bf16 v[16:19], v[212:215], v[196:199], v[16:19]
	v_mfma_f32_16x16x32_bf16 v[12:15], v[220:223], v[196:199], v[12:15]
	v_mfma_f32_16x16x32_bf16 v[8:11], v[212:215], v[204:207], v[8:11]
	v_mfma_f32_16x16x32_bf16 v[4:7], v[220:223], v[204:207], v[4:7]
	v_mfma_f32_16x16x32_bf16 v[48:51], v[216:219], v[184:187], v[48:51]
	v_mfma_f32_16x16x32_bf16 v[44:47], v[224:227], v[184:187], v[44:47]
	v_mfma_f32_16x16x32_bf16 v[32:35], v[216:219], v[192:195], v[32:35]
	v_mfma_f32_16x16x32_bf16 v[28:31], v[224:227], v[192:195], v[28:31]
	v_mfma_f32_16x16x32_bf16 v[16:19], v[216:219], v[200:203], v[16:19]
	v_mfma_f32_16x16x32_bf16 v[12:15], v[224:227], v[200:203], v[12:15]
	v_mfma_f32_16x16x32_bf16 v[8:11], v[216:219], v[208:211], v[8:11]
	v_mfma_f32_16x16x32_bf16 v[4:7], v[224:227], v[208:211], v[4:7]
	s_setprio 0
	s_add_i32 s69, 0, 0x18000
	s_barrier
	ds_read_b128 v[148:151], v228 offset:32768
	ds_read_b128 v[152:155], v228 offset:33792
	ds_read_b128 v[156:159], v228 offset:34816
	ds_read_b128 v[176:179], v228 offset:35840
	s_add_u32 s4, s4, 0x4000
	s_addc_u32 s5, s5, 0
	s_mov_b32 m0, s60
	ds_read_b128 v[180:183], v146 offset:32768
	ds_read_b128 v[184:187], v146 offset:33792
	ds_read_b128 v[188:191], v146 offset:34816
	ds_read_b128 v[192:195], v146 offset:35840
	ds_read_b128 v[196:199], v146 offset:36864
	ds_read_b128 v[200:203], v146 offset:37888
	ds_read_b128 v[204:207], v146 offset:38912
	ds_read_b128 v[208:211], v146 offset:39936
	global_load_lds_dwordx4 v132, s[4:5]
	s_mov_b32 m0, s61
	s_nop 0
	global_load_lds_dwordx4 v138, s[4:5]
	s_waitcnt lgkmcnt(8)
	s_barrier
	s_waitcnt lgkmcnt(0)
	s_setprio 1
	v_mfma_f32_16x16x32_bf16 v[128:131], v[148:151], v[180:183], v[128:131]
	v_mfma_f32_16x16x32_bf16 v[124:127], v[156:159], v[180:183], v[124:127]
	v_mfma_f32_16x16x32_bf16 v[120:123], v[148:151], v[188:191], v[120:123]
	v_mfma_f32_16x16x32_bf16 v[116:119], v[156:159], v[188:191], v[116:119]
	v_mfma_f32_16x16x32_bf16 v[104:107], v[148:151], v[196:199], v[104:107]
	v_mfma_f32_16x16x32_bf16 v[100:103], v[156:159], v[196:199], v[100:103]
	v_mfma_f32_16x16x32_bf16 v[88:91], v[148:151], v[204:207], v[88:91]
	v_mfma_f32_16x16x32_bf16 v[84:87], v[156:159], v[204:207], v[84:87]
	v_mfma_f32_16x16x32_bf16 v[128:131], v[152:155], v[184:187], v[128:131]
	v_mfma_f32_16x16x32_bf16 v[124:127], v[176:179], v[184:187], v[124:127]
	v_mfma_f32_16x16x32_bf16 v[120:123], v[152:155], v[192:195], v[120:123]
	v_mfma_f32_16x16x32_bf16 v[116:119], v[176:179], v[192:195], v[116:119]
	v_mfma_f32_16x16x32_bf16 v[104:107], v[152:155], v[200:203], v[104:107]
	v_mfma_f32_16x16x32_bf16 v[100:103], v[176:179], v[200:203], v[100:103]
	s_setprio 2
	s_barrier
	v_mfma_f32_16x16x32_bf16 v[88:91], v[152:155], v[208:211], v[88:91]
	v_mfma_f32_16x16x32_bf16 v[84:87], v[176:179], v[208:211], v[84:87]
	s_setprio 0
	s_add_i32 s70, 0, 0x1c000
	s_add_u32 s4, s56, 0x8000
	s_addc_u32 s5, s57, 0
	s_add_i32 s69, s69, s39
	ds_read_b128 v[212:215], v228 offset:49152
	ds_read_b128 v[216:219], v228 offset:50176
	ds_read_b128 v[220:223], v228 offset:51200
	ds_read_b128 v[224:227], v228 offset:52224
	s_mov_b32 m0, s69
	s_nop 0
	global_load_lds_dwordx4 v132, s[4:5]
	s_add_i32 m0, s69, 0x2000
	s_nop 0
	global_load_lds_dwordx4 v138, s[4:5]
	s_barrier
	s_waitcnt lgkmcnt(0)
	s_setprio 1
	v_mfma_f32_16x16x32_bf16 v[112:115], v[212:215], v[180:183], v[112:115]
	v_mfma_f32_16x16x32_bf16 v[108:111], v[220:223], v[180:183], v[108:111]
	v_mfma_f32_16x16x32_bf16 v[96:99], v[212:215], v[188:191], v[96:99]
	v_mfma_f32_16x16x32_bf16 v[92:95], v[220:223], v[188:191], v[92:95]
	v_mfma_f32_16x16x32_bf16 v[80:83], v[212:215], v[196:199], v[80:83]
	v_mfma_f32_16x16x32_bf16 v[76:79], v[220:223], v[196:199], v[76:79]
	v_mfma_f32_16x16x32_bf16 v[72:75], v[212:215], v[204:207], v[72:75]
	v_mfma_f32_16x16x32_bf16 v[68:71], v[220:223], v[204:207], v[68:71]
	v_mfma_f32_16x16x32_bf16 v[112:115], v[216:219], v[184:187], v[112:115]
	v_mfma_f32_16x16x32_bf16 v[108:111], v[224:227], v[184:187], v[108:111]
	v_mfma_f32_16x16x32_bf16 v[96:99], v[216:219], v[192:195], v[96:99]
	v_mfma_f32_16x16x32_bf16 v[92:95], v[224:227], v[192:195], v[92:95]
	v_mfma_f32_16x16x32_bf16 v[80:83], v[216:219], v[200:203], v[80:83]
	v_mfma_f32_16x16x32_bf16 v[76:79], v[224:227], v[200:203], v[76:79]
	v_mfma_f32_16x16x32_bf16 v[72:75], v[216:219], v[208:211], v[72:75]
	v_mfma_f32_16x16x32_bf16 v[68:71], v[224:227], v[208:211], v[68:71]
	s_setprio 0
	s_mov_b32 m0, s64
	s_barrier
	ds_read_b128 v[180:183], v146 offset:49152
	ds_read_b128 v[184:187], v146 offset:50176
	ds_read_b128 v[188:191], v146 offset:51200
	ds_read_b128 v[192:195], v146 offset:52224
	ds_read_b128 v[196:199], v146 offset:53248
	ds_read_b128 v[200:203], v146 offset:54272
	ds_read_b128 v[204:207], v146 offset:55296
	ds_read_b128 v[208:211], v146 offset:56320
	global_load_lds_dwordx4 v132, s[58:59]
	s_mov_b32 m0, s65
	s_nop 0
	global_load_lds_dwordx4 v138, s[58:59]
	s_barrier
; #define PG8_STAGE(bufoff, gbase, voff) do { _Pragma("unroll") for (int _i = 0; _i < 2; ++_i) \
;         __builtin_amdgcn_global_load_lds((const unsigned*)((const char*)(gbase) + (voff)[_i]), (LAS unsigned*)(lds + (bufoff) + ldsw + _i * 8192), 16, 0, 0); } while (0)
; #define PG8_MMA(ai, bj, At, Bt) do { __builtin_amdgcn_s_setprio(1); _Pragma("unroll") for (int m = 0; m < 4; ++m) _Pragma("unroll") for (int n = 0; n < 2; ++n) _Pragma("unroll") for (int k = 0; k < 2; ++k) \
;         acc[ai][bj][m][n] = __builtin_amdgcn_mfma_f32_16x16x32_bf16(Bt[n][k], At[m][k], acc[ai][bj][m][n], 0, 0, 0); __builtin_amdgcn_s_setprio(0); } while (0)
; #define PG8_WAIT_V(n) asm volatile("s_waitcnt vmcnt(" #n ")" ::: "memory")
; #define PG8_WAIT_L(n) asm volatile("s_waitcnt lgkmcnt(" #n ")" ::: "memory")
; #define PG8_BAR __builtin_amdgcn_s_barrier()
; #define PG8_SCHED __builtin_amdgcn_sched_barrier(0)
;     __device__ __forceinline__ void operator()(const f32x4 (&acc)[2][2][4][2], const Unit& u, int wr, int wc, int fr, int fq) const {
;     ...
;         } else if (wc == 0) {
; #pragma unroll
;             for (int ai = 0; ai < 2; ++ai)
; #pragma unroll
;                 for (int m = 0; m < 4; ++m) {
;                     float* rowp = DT + (size_t)(row0 + ai * HALF + m * 16) * 32 + 8 * fq;
;                     *(f32x4*)rowp = acc[ai][0][m][0]; *(f32x4*)(rowp + 4) = acc[ai][0][m][1];
;                 }
; template <class Epi, class Sched, int LD>
; __device__ __forceinline__ void gemm_phase(LAS unsigned char* lds, const Gemm g, const Sched& S, const Epi& E) {
;     ...
;             PG8_BAR; PG8_WAIT_L(0); PG8_MMA(1, 0, At, B0); PG8_BAR; PG8_SCHED;
;             PG8_STAGE(PG8_SB(1, 1), b3 + hstep, voffB);
;             PG8_WAIT_V(6); PG8_BAR; PG8_MMA(1, 1, At, B1); PG8_BAR;
;         }
	s_waitcnt lgkmcnt(0)
	s_setprio 1
	v_mfma_f32_16x16x32_bf16 v[64:67], v[148:151], v[180:183], v[64:67]
	v_mfma_f32_16x16x32_bf16 v[60:63], v[156:159], v[180:183], v[60:63]
	v_mfma_f32_16x16x32_bf16 v[56:59], v[148:151], v[188:191], v[56:59]
	v_mfma_f32_16x16x32_bf16 v[52:55], v[156:159], v[188:191], v[52:55]
	v_mfma_f32_16x16x32_bf16 v[40:43], v[148:151], v[196:199], v[40:43]
	v_mfma_f32_16x16x32_bf16 v[36:39], v[156:159], v[196:199], v[36:39]
	v_mfma_f32_16x16x32_bf16 v[24:27], v[148:151], v[204:207], v[24:27]
	v_mfma_f32_16x16x32_bf16 v[20:23], v[156:159], v[204:207], v[20:23]
	v_mfma_f32_16x16x32_bf16 v[64:67], v[152:155], v[184:187], v[64:67]
	v_mfma_f32_16x16x32_bf16 v[60:63], v[176:179], v[184:187], v[60:63]
	v_mfma_f32_16x16x32_bf16 v[56:59], v[152:155], v[192:195], v[56:59]
	v_mfma_f32_16x16x32_bf16 v[52:55], v[176:179], v[192:195], v[52:55]
	v_mfma_f32_16x16x32_bf16 v[40:43], v[152:155], v[200:203], v[40:43]
	v_mfma_f32_16x16x32_bf16 v[36:39], v[176:179], v[200:203], v[36:39]
	s_setprio 2
	s_barrier
	v_mfma_f32_16x16x32_bf16 v[24:27], v[152:155], v[208:211], v[24:27]
	v_mfma_f32_16x16x32_bf16 v[20:23], v[176:179], v[208:211], v[20:23]
	s_setprio 0
	s_add_u32 s4, s56, 0xc000
	s_addc_u32 s5, s57, 0
	s_add_i32 s56, s70, s39
	s_mov_b32 m0, s56
	s_nop 0
	global_load_lds_dwordx4 v132, s[4:5]
	s_add_i32 m0, s56, 0x2000
	s_nop 0
	global_load_lds_dwordx4 v138, s[4:5]
	s_waitcnt vmcnt(6)
	s_barrier
	s_setprio 1
	v_mfma_f32_16x16x32_bf16 v[48:51], v[212:215], v[180:183], v[48:51]
	v_mfma_f32_16x16x32_bf16 v[44:47], v[220:223], v[180:183], v[44:47]
	v_mfma_f32_16x16x32_bf16 v[32:35], v[212:215], v[188:191], v[32:35]
	v_mfma_f32_16x16x32_bf16 v[28:31], v[220:223], v[188:191], v[28:31]
	v_mfma_f32_16x16x32_bf16 v[16:19], v[212:215], v[196:199], v[16:19]
	v_mfma_f32_16x16x32_bf16 v[12:15], v[220:223], v[196:199], v[12:15]
	v_mfma_f32_16x16x32_bf16 v[8:11], v[212:215], v[204:207], v[8:11]
	v_mfma_f32_16x16x32_bf16 v[4:7], v[220:223], v[204:207], v[4:7]
	v_mfma_f32_16x16x32_bf16 v[48:51], v[216:219], v[184:187], v[48:51]
	v_mfma_f32_16x16x32_bf16 v[44:47], v[224:227], v[184:187], v[44:47]
	v_mfma_f32_16x16x32_bf16 v[32:35], v[216:219], v[192:195], v[32:35]
	v_mfma_f32_16x16x32_bf16 v[28:31], v[224:227], v[192:195], v[28:31]
	v_mfma_f32_16x16x32_bf16 v[16:19], v[216:219], v[200:203], v[16:19]
	v_mfma_f32_16x16x32_bf16 v[12:15], v[224:227], v[200:203], v[12:15]
	v_mfma_f32_16x16x32_bf16 v[8:11], v[216:219], v[208:211], v[8:11]
	v_mfma_f32_16x16x32_bf16 v[4:7], v[224:227], v[208:211], v[4:7]
	s_setprio 0
	s_add_i32 s49, s49, 2
	s_add_u32 s54, s54, 0x10000
	s_addc_u32 s55, s55, 0
	s_add_u32 s29, s29, 0x10000
	s_addc_u32 s47, s47, 0
	s_cmp_gt_u32 s49, 29
	s_barrier
	s_cbranch_scc0 .LBB0_501
	v_lshl_add_u32 v142, s68, 8, v137
	s_cmp_gt_i32 s67, 35
	s_mov_b64 s[4:5], -1
	s_cbranch_scc0 .LBB0_506
	s_andn2_b64 vcc, exec, s[42:43]
	s_cbranch_vccnz .LBB0_505
	v_or_b32_e32 v150, 16, v142
	v_ashrrev_i32_e32 v143, 31, v142
	v_ashrrev_i32_e32 v151, 31, v150
	v_lshlrev_b64 v[148:149], 7, v[142:143]
	v_lshlrev_b64 v[150:151], 7, v[150:151]
	v_lshl_add_u64 v[148:149], v[140:141], 0, v[148:149]
	v_lshl_add_u64 v[150:151], v[140:141], 0, v[150:151]
	global_store_dwordx4 v[148:149], v[128:131], off
	global_store_dwordx4 v[148:149], v[124:127], off offset:16
	global_store_dwordx4 v[150:151], v[120:123], off
	global_store_dwordx4 v[150:151], v[116:119], off offset:16
	v_or_b32_e32 v150, 32, v142
	v_ashrrev_i32_e32 v151, 31, v150
	v_lshlrev_b64 v[150:151], 7, v[150:151]
	v_lshl_add_u64 v[150:151], v[140:141], 0, v[150:151]
	global_store_dwordx4 v[150:151], v[104:107], off
	global_store_dwordx4 v[150:151], v[100:103], off offset:16
	v_or_b32_e32 v150, 48, v142
	v_ashrrev_i32_e32 v151, 31, v150
	v_lshlrev_b64 v[150:151], 7, v[150:151]
	v_lshl_add_u64 v[150:151], v[140:141], 0, v[150:151]
	s_mov_b64 s[4:5], 0x4000
	global_store_dwordx4 v[150:151], v[88:91], off
	global_store_dwordx4 v[150:151], v[84:87], off offset:16
	v_lshl_add_u64 v[150:151], v[148:149], 0, s[4:5]
	s_movk_i32 s4, 0x4000
	v_add_co_u32_e32 v152, vcc, s4, v148
	s_mov_b64 s[4:5], 0x4800
	s_nop 0
	v_addc_co_u32_e32 v153, vcc, 0, v149, vcc
	global_store_dwordx4 v[152:153], v[64:67], off
	global_store_dwordx4 v[150:151], v[60:63], off offset:16
	v_lshl_add_u64 v[150:151], v[148:149], 0, s[4:5]
	global_store_dwordx4 v[152:153], v[56:59], off offset:2048
	global_store_dwordx4 v[150:151], v[52:55], off offset:16
	s_mov_b64 s[4:5], 0x5000
	v_add_co_u32_e32 v152, vcc, 0x5000, v148
	v_lshl_add_u64 v[150:151], v[148:149], 0, s[4:5]
	s_nop 0
	v_addc_co_u32_e32 v153, vcc, 0, v149, vcc
	s_mov_b64 s[4:5], 0x5800
	global_store_dwordx4 v[152:153], v[40:43], off
	global_store_dwordx4 v[150:151], v[36:39], off offset:16
	v_lshl_add_u64 v[148:149], v[148:149], 0, s[4:5]
	global_store_dwordx4 v[152:153], v[24:27], off offset:2048
	global_store_dwordx4 v[148:149], v[20:23], off offset:16

; #define PG8_STAGE(bufoff, gbase, voff) do { _Pragma("unroll") for (int _i = 0; _i < 2; ++_i) \
;         __builtin_amdgcn_global_load_lds((const unsigned*)((const char*)(gbase) + (voff)[_i]), (LAS unsigned*)(lds + (bufoff) + ldsw + _i * 8192), 16, 0, 0); } while (0)
; #define PG8_LDA(dst, b, h) do { _Pragma("unroll") for (int m = 0; m < 4; ++m) _Pragma("unroll") for (int k = 0; k < 2; ++k) dst[m][k] = *(const LAS bf16x8*)(lds + PG8_SA(b, h) + aoff + m * 2048 + k * 1024); } while (0)
; #define PG8_LDB(dst, b, h) do { _Pragma("unroll") for (int n = 0; n < 2; ++n) _Pragma("unroll") for (int k = 0; k < 2; ++k) dst[n][k] = *(const LAS bf16x8*)(lds + PG8_SB(b, h) + boff + n * 2048 + k * 1024); } while (0)
; #define PG8_MMA(ai, bj, At, Bt) do { __builtin_amdgcn_s_setprio(1); _Pragma("unroll") for (int m = 0; m < 4; ++m) _Pragma("unroll") for (int n = 0; n < 2; ++n) _Pragma("unroll") for (int k = 0; k < 2; ++k) \
;         acc[ai][bj][m][n] = __builtin_amdgcn_mfma_f32_16x16x32_bf16(Bt[n][k], At[m][k], acc[ai][bj][m][n], 0, 0, 0); __builtin_amdgcn_s_setprio(0); } while (0)
; #define PG8_WAIT_L(n) asm volatile("s_waitcnt lgkmcnt(" #n ")" ::: "memory")
; #define PG8_BAR __builtin_amdgcn_s_barrier()
; #define PG8_SCHED __builtin_amdgcn_sched_barrier(0)
; template <class Epi, class Sched, int LD>
; __device__ __forceinline__ void gemm_phase(LAS unsigned char* lds, const Gemm g, const Sched& S, const Epi& E) {
;     ...
;         for (int t = 0; t < nt; t += 2) {
;             const bool last = (t == nt - 2);
;             const char* a1 = cA + (size_t)(t + 1) * kstep;
;             const char* a2 = last ? nA : cA + (size_t)(t + 2) * kstep; const char* b2 = last ? nB : cB + (size_t)(t + 2) * kstep;
;             const char* a3 = a2 + kstep; const char* b3 = b2 + kstep;
;             PG8_LDB(B0, 0, 0); PG8_SCHED; PG8_LDA(At, 0, 0); PG8_STAGE(PG8_SA(1, 1), a1 + hstep, voffA);
;             PG8_WAIT_L(8); PG8_BAR; PG8_WAIT_L(0); PG8_MMA(0, 0, At, B0); PG8_BAR; PG8_SCHED;
;             PG8_LDB(B1, 0, 1); PG8_STAGE(PG8_SB(0, 0), b2, voffB);
;             PG8_BAR; PG8_WAIT_L(0); PG8_MMA(0, 1, At, B1); PG8_BAR;
;             PG8_LDA(At, 0, 1); PG8_STAGE(PG8_SA(0, 0), a2, voffA);
;             PG8_BAR; PG8_WAIT_L(0); PG8_MMA(1, 0, At, B0); PG8_BAR; PG8_SCHED;
;             PG8_STAGE(PG8_SB(0, 1), b2 + hstep, voffB);
.LBB0_899:
	s_add_u32 s4, s50, 0x4000
	s_addc_u32 s5, s51, 0
	s_cmp_eq_u32 s70, 28
	s_cselect_b32 s4, s48, s4
	s_cselect_b32 s5, s49, s5
	s_cselect_b32 s54, s40, s45
	s_cselect_b32 s55, s41, s47
	s_add_u32 s56, s4, 0x8000
	s_addc_u32 s57, s5, 0
	s_add_i32 s71, 0, 0x10000
	ds_read_b128 v[146:149], v228
	ds_read_b128 v[150:153], v228 offset:1024
	ds_read_b128 v[154:157], v228 offset:2048
	ds_read_b128 v[176:179], v228 offset:3072
	s_add_i32 m0, s29, 0xc000
	ds_read_b128 v[180:183], v144
	ds_read_b128 v[184:187], v144 offset:1024
	ds_read_b128 v[188:191], v144 offset:2048
	ds_read_b128 v[192:195], v144 offset:3072
	ds_read_b128 v[196:199], v144 offset:4096
	ds_read_b128 v[200:203], v144 offset:5120
	ds_read_b128 v[204:207], v144 offset:6144
	ds_read_b128 v[208:211], v144 offset:7168
	global_load_lds_dwordx4 v138, s[50:51]
	s_add_i32 m0, s29, 0xe000
	s_nop 0
	global_load_lds_dwordx4 v140, s[50:51]
	s_waitcnt lgkmcnt(8)
	s_barrier
	s_waitcnt lgkmcnt(0)
	s_setprio 1
	v_mfma_f32_16x16x32_bf16 v[128:131], v[146:149], v[180:183], v[128:131]
	v_mfma_f32_16x16x32_bf16 v[120:123], v[154:157], v[180:183], v[120:123]
	v_mfma_f32_16x16x32_bf16 v[112:115], v[146:149], v[188:191], v[112:115]
	v_mfma_f32_16x16x32_bf16 v[104:107], v[154:157], v[188:191], v[104:107]
	v_mfma_f32_16x16x32_bf16 v[96:99], v[146:149], v[196:199], v[96:99]
	v_mfma_f32_16x16x32_bf16 v[88:91], v[154:157], v[196:199], v[88:91]
	v_mfma_f32_16x16x32_bf16 v[80:83], v[146:149], v[204:207], v[80:83]
	v_mfma_f32_16x16x32_bf16 v[72:75], v[154:157], v[204:207], v[72:75]
	v_mfma_f32_16x16x32_bf16 v[128:131], v[150:153], v[184:187], v[128:131]
	v_mfma_f32_16x16x32_bf16 v[120:123], v[176:179], v[184:187], v[120:123]
	v_mfma_f32_16x16x32_bf16 v[112:115], v[150:153], v[192:195], v[112:115]
	v_mfma_f32_16x16x32_bf16 v[104:107], v[176:179], v[192:195], v[104:107]
	v_mfma_f32_16x16x32_bf16 v[96:99], v[150:153], v[200:203], v[96:99]
	v_mfma_f32_16x16x32_bf16 v[88:91], v[176:179], v[200:203], v[88:91]
	s_setprio 2
	s_barrier
	v_mfma_f32_16x16x32_bf16 v[80:83], v[150:153], v[208:211], v[80:83]
	v_mfma_f32_16x16x32_bf16 v[72:75], v[176:179], v[208:211], v[72:75]
	s_setprio 0
	s_add_i32 s74, 0, 0x14000
	s_add_i32 s71, s71, s28
	s_mov_b32 m0, s71
	ds_read_b128 v[212:215], v228 offset:16384
	ds_read_b128 v[216:219], v228 offset:17408
	ds_read_b128 v[220:223], v228 offset:18432
	ds_read_b128 v[224:227], v228 offset:19456
	global_load_lds_dwordx4 v138, s[54:55]
	s_add_i32 m0, s71, 0x2000
	s_nop 0
	global_load_lds_dwordx4 v140, s[54:55]
	s_barrier
	s_waitcnt lgkmcnt(0)
	s_setprio 1
	v_mfma_f32_16x16x32_bf16 v[124:127], v[212:215], v[180:183], v[124:127]
	v_mfma_f32_16x16x32_bf16 v[116:119], v[220:223], v[180:183], v[116:119]
	v_mfma_f32_16x16x32_bf16 v[108:111], v[212:215], v[188:191], v[108:111]
	v_mfma_f32_16x16x32_bf16 v[100:103], v[220:223], v[188:191], v[100:103]
	v_mfma_f32_16x16x32_bf16 v[92:95], v[212:215], v[196:199], v[92:95]
	v_mfma_f32_16x16x32_bf16 v[84:87], v[220:223], v[196:199], v[84:87]
	v_mfma_f32_16x16x32_bf16 v[76:79], v[212:215], v[204:207], v[76:79]
	v_mfma_f32_16x16x32_bf16 v[68:71], v[220:223], v[204:207], v[68:71]
	v_mfma_f32_16x16x32_bf16 v[124:127], v[216:219], v[184:187], v[124:127]
	v_mfma_f32_16x16x32_bf16 v[116:119], v[224:227], v[184:187], v[116:119]
	v_mfma_f32_16x16x32_bf16 v[108:111], v[216:219], v[192:195], v[108:111]
	v_mfma_f32_16x16x32_bf16 v[100:103], v[224:227], v[192:195], v[100:103]
	v_mfma_f32_16x16x32_bf16 v[92:95], v[216:219], v[200:203], v[92:95]
	v_mfma_f32_16x16x32_bf16 v[84:87], v[224:227], v[200:203], v[84:87]
	v_mfma_f32_16x16x32_bf16 v[76:79], v[216:219], v[208:211], v[76:79]
	v_mfma_f32_16x16x32_bf16 v[68:71], v[224:227], v[208:211], v[68:71]
	s_setprio 0
	s_mov_b32 m0, s29
	s_barrier
	ds_read_b128 v[180:183], v144 offset:16384
	ds_read_b128 v[184:187], v144 offset:17408
	ds_read_b128 v[188:191], v144 offset:18432
	ds_read_b128 v[192:195], v144 offset:19456
	ds_read_b128 v[196:199], v144 offset:20480
	ds_read_b128 v[200:203], v144 offset:21504
	ds_read_b128 v[204:207], v144 offset:22528
	ds_read_b128 v[208:211], v144 offset:23552
	global_load_lds_dwordx4 v138, s[4:5]
	s_mov_b32 m0, s39
	s_nop 0
	global_load_lds_dwordx4 v140, s[4:5]
	s_barrier
	s_waitcnt lgkmcnt(0)
	s_setprio 1
	v_mfma_f32_16x16x32_bf16 v[64:67], v[146:149], v[180:183], v[64:67]
	v_mfma_f32_16x16x32_bf16 v[56:59], v[154:157], v[180:183], v[56:59]
	v_mfma_f32_16x16x32_bf16 v[48:51], v[146:149], v[188:191], v[48:51]
	v_mfma_f32_16x16x32_bf16 v[40:43], v[154:157], v[188:191], v[40:43]
	v_mfma_f32_16x16x32_bf16 v[32:35], v[146:149], v[196:199], v[32:35]
	v_mfma_f32_16x16x32_bf16 v[24:27], v[154:157], v[196:199], v[24:27]
	v_mfma_f32_16x16x32_bf16 v[16:19], v[146:149], v[204:207], v[16:19]
	v_mfma_f32_16x16x32_bf16 v[8:11], v[154:157], v[204:207], v[8:11]
	v_mfma_f32_16x16x32_bf16 v[64:67], v[150:153], v[184:187], v[64:67]
	v_mfma_f32_16x16x32_bf16 v[56:59], v[176:179], v[184:187], v[56:59]
	v_mfma_f32_16x16x32_bf16 v[48:51], v[150:153], v[192:195], v[48:51]
	v_mfma_f32_16x16x32_bf16 v[40:43], v[176:179], v[192:195], v[40:43]
	v_mfma_f32_16x16x32_bf16 v[32:35], v[150:153], v[200:203], v[32:35]
	v_mfma_f32_16x16x32_bf16 v[24:27], v[176:179], v[200:203], v[24:27]
	s_setprio 2
	s_barrier
	v_mfma_f32_16x16x32_bf16 v[16:19], v[150:153], v[208:211], v[16:19]
	v_mfma_f32_16x16x32_bf16 v[8:11], v[176:179], v[208:211], v[8:11]
	s_setprio 0
	s_add_u32 s72, s54, 0x4000
	s_addc_u32 s73, s55, 0
	s_add_i32 s71, s74, s28
	s_mov_b32 m0, s71
	s_nop 0
	global_load_lds_dwordx4 v138, s[72:73]
	s_add_i32 m0, s71, 0x2000
	s_nop 0
	global_load_lds_dwordx4 v140, s[72:73]
	s_waitcnt vmcnt(6)
	s_barrier
; #define PG8_STAGE(bufoff, gbase, voff) do { _Pragma("unroll") for (int _i = 0; _i < 2; ++_i) \
;         __builtin_amdgcn_global_load_lds((const unsigned*)((const char*)(gbase) + (voff)[_i]), (LAS unsigned*)(lds + (bufoff) + ldsw + _i * 8192), 16, 0, 0); } while (0)
; #define PG8_LDA(dst, b, h) do { _Pragma("unroll") for (int m = 0; m < 4; ++m) _Pragma("unroll") for (int k = 0; k < 2; ++k) dst[m][k] = *(const LAS bf16x8*)(lds + PG8_SA(b, h) + aoff + m * 2048 + k * 1024); } while (0)
; #define PG8_LDB(dst, b, h) do { _Pragma("unroll") for (int n = 0; n < 2; ++n) _Pragma("unroll") for (int k = 0; k < 2; ++k) dst[n][k] = *(const LAS bf16x8*)(lds + PG8_SB(b, h) + boff + n * 2048 + k * 1024); } while (0)
; #define PG8_MMA(ai, bj, At, Bt) do { __builtin_amdgcn_s_setprio(1); _Pragma("unroll") for (int m = 0; m < 4; ++m) _Pragma("unroll") for (int n = 0; n < 2; ++n) _Pragma("unroll") for (int k = 0; k < 2; ++k) \
;         acc[ai][bj][m][n] = __builtin_amdgcn_mfma_f32_16x16x32_bf16(Bt[n][k], At[m][k], acc[ai][bj][m][n], 0, 0, 0); __builtin_amdgcn_s_setprio(0); } while (0)
; #define PG8_WAIT_V(n) asm volatile("s_waitcnt vmcnt(" #n ")" ::: "memory")
; #define PG8_WAIT_L(n) asm volatile("s_waitcnt lgkmcnt(" #n ")" ::: "memory")
; #define PG8_BAR __builtin_amdgcn_s_barrier()
; #define PG8_SCHED __builtin_amdgcn_sched_barrier(0)
; template <class Epi, class Sched, int LD>
; __device__ __forceinline__ void gemm_phase(LAS unsigned char* lds, const Gemm g, const Sched& S, const Epi& E) {
;     ...
;             PG8_WAIT_V(6); PG8_BAR; PG8_MMA(1, 1, At, B1); PG8_BAR;
;             PG8_LDB(B0, 1, 0); PG8_SCHED; PG8_LDA(At, 1, 0); PG8_STAGE(PG8_SA(0, 1), a2 + hstep, voffA);
;             PG8_WAIT_L(8); PG8_BAR; PG8_WAIT_L(0); PG8_MMA(0, 0, At, B0); PG8_BAR; PG8_SCHED;
;             PG8_LDB(B1, 1, 1); PG8_STAGE(PG8_SB(1, 0), b3, voffB);
;             PG8_BAR; PG8_WAIT_L(0); PG8_MMA(0, 1, At, B1); PG8_BAR;
;             PG8_LDA(At, 1, 1); PG8_STAGE(PG8_SA(1, 0), a3, voffA);
	s_setprio 1
	v_mfma_f32_16x16x32_bf16 v[60:63], v[212:215], v[180:183], v[60:63]
	v_mfma_f32_16x16x32_bf16 v[52:55], v[220:223], v[180:183], v[52:55]
	v_mfma_f32_16x16x32_bf16 v[44:47], v[212:215], v[188:191], v[44:47]
	v_mfma_f32_16x16x32_bf16 v[36:39], v[220:223], v[188:191], v[36:39]
	v_mfma_f32_16x16x32_bf16 v[28:31], v[212:215], v[196:199], v[28:31]
	v_mfma_f32_16x16x32_bf16 v[20:23], v[220:223], v[196:199], v[20:23]
	v_mfma_f32_16x16x32_bf16 v[12:15], v[212:215], v[204:207], v[12:15]
	v_mfma_f32_16x16x32_bf16 v[4:7], v[220:223], v[204:207], v[4:7]
	v_mfma_f32_16x16x32_bf16 v[60:63], v[216:219], v[184:187], v[60:63]
	v_mfma_f32_16x16x32_bf16 v[52:55], v[224:227], v[184:187], v[52:55]
	v_mfma_f32_16x16x32_bf16 v[44:47], v[216:219], v[192:195], v[44:47]
	v_mfma_f32_16x16x32_bf16 v[36:39], v[224:227], v[192:195], v[36:39]
	v_mfma_f32_16x16x32_bf16 v[28:31], v[216:219], v[200:203], v[28:31]
	v_mfma_f32_16x16x32_bf16 v[20:23], v[224:227], v[200:203], v[20:23]
	v_mfma_f32_16x16x32_bf16 v[12:15], v[216:219], v[208:211], v[12:15]
	v_mfma_f32_16x16x32_bf16 v[4:7], v[224:227], v[208:211], v[4:7]
	s_setprio 0
	s_add_i32 s71, 0, 0x18000
	s_barrier
	ds_read_b128 v[146:149], v228 offset:32768
	ds_read_b128 v[150:153], v228 offset:33792
	ds_read_b128 v[154:157], v228 offset:34816
	ds_read_b128 v[176:179], v228 offset:35840
	s_add_u32 s4, s4, 0x4000
	s_addc_u32 s5, s5, 0
	s_mov_b32 m0, s52
	ds_read_b128 v[180:183], v144 offset:32768
	ds_read_b128 v[184:187], v144 offset:33792
	ds_read_b128 v[188:191], v144 offset:34816
	ds_read_b128 v[192:195], v144 offset:35840
	ds_read_b128 v[196:199], v144 offset:36864
	ds_read_b128 v[200:203], v144 offset:37888
	ds_read_b128 v[204:207], v144 offset:38912
	ds_read_b128 v[208:211], v144 offset:39936
	global_load_lds_dwordx4 v138, s[4:5]
	s_mov_b32 m0, s53
	s_nop 0
	global_load_lds_dwordx4 v140, s[4:5]
	s_waitcnt lgkmcnt(8)
	s_barrier
	s_waitcnt lgkmcnt(0)
	s_setprio 1
	v_mfma_f32_16x16x32_bf16 v[128:131], v[146:149], v[180:183], v[128:131]
	v_mfma_f32_16x16x32_bf16 v[120:123], v[154:157], v[180:183], v[120:123]
	v_mfma_f32_16x16x32_bf16 v[112:115], v[146:149], v[188:191], v[112:115]
	v_mfma_f32_16x16x32_bf16 v[104:107], v[154:157], v[188:191], v[104:107]
	v_mfma_f32_16x16x32_bf16 v[96:99], v[146:149], v[196:199], v[96:99]
	v_mfma_f32_16x16x32_bf16 v[88:91], v[154:157], v[196:199], v[88:91]
	v_mfma_f32_16x16x32_bf16 v[80:83], v[146:149], v[204:207], v[80:83]
	v_mfma_f32_16x16x32_bf16 v[72:75], v[154:157], v[204:207], v[72:75]
	v_mfma_f32_16x16x32_bf16 v[128:131], v[150:153], v[184:187], v[128:131]
	v_mfma_f32_16x16x32_bf16 v[120:123], v[176:179], v[184:187], v[120:123]
	v_mfma_f32_16x16x32_bf16 v[112:115], v[150:153], v[192:195], v[112:115]
	v_mfma_f32_16x16x32_bf16 v[104:107], v[176:179], v[192:195], v[104:107]
	v_mfma_f32_16x16x32_bf16 v[96:99], v[150:153], v[200:203], v[96:99]
	v_mfma_f32_16x16x32_bf16 v[88:91], v[176:179], v[200:203], v[88:91]
	s_setprio 2
	s_barrier
	v_mfma_f32_16x16x32_bf16 v[80:83], v[150:153], v[208:211], v[80:83]
	v_mfma_f32_16x16x32_bf16 v[72:75], v[176:179], v[208:211], v[72:75]
	s_setprio 0
	s_add_i32 s72, 0, 0x1c000
	s_add_u32 s4, s54, 0x8000
	s_addc_u32 s5, s55, 0
	s_add_i32 s71, s71, s28
	s_mov_b32 m0, s71
	ds_read_b128 v[212:215], v228 offset:49152
	ds_read_b128 v[216:219], v228 offset:50176
	ds_read_b128 v[220:223], v228 offset:51200
	ds_read_b128 v[224:227], v228 offset:52224
	global_load_lds_dwordx4 v138, s[4:5]
	s_add_i32 m0, s71, 0x2000
	s_nop 0
	global_load_lds_dwordx4 v140, s[4:5]
	s_barrier
	s_waitcnt lgkmcnt(0)
	s_setprio 1
	v_mfma_f32_16x16x32_bf16 v[124:127], v[212:215], v[180:183], v[124:127]
	v_mfma_f32_16x16x32_bf16 v[116:119], v[220:223], v[180:183], v[116:119]
	v_mfma_f32_16x16x32_bf16 v[108:111], v[212:215], v[188:191], v[108:111]
	v_mfma_f32_16x16x32_bf16 v[100:103], v[220:223], v[188:191], v[100:103]
	v_mfma_f32_16x16x32_bf16 v[92:95], v[212:215], v[196:199], v[92:95]
	v_mfma_f32_16x16x32_bf16 v[84:87], v[220:223], v[196:199], v[84:87]
	v_mfma_f32_16x16x32_bf16 v[76:79], v[212:215], v[204:207], v[76:79]
	v_mfma_f32_16x16x32_bf16 v[68:71], v[220:223], v[204:207], v[68:71]
	v_mfma_f32_16x16x32_bf16 v[124:127], v[216:219], v[184:187], v[124:127]
	v_mfma_f32_16x16x32_bf16 v[116:119], v[224:227], v[184:187], v[116:119]
	v_mfma_f32_16x16x32_bf16 v[108:111], v[216:219], v[192:195], v[108:111]
	v_mfma_f32_16x16x32_bf16 v[100:103], v[224:227], v[192:195], v[100:103]
	v_mfma_f32_16x16x32_bf16 v[92:95], v[216:219], v[200:203], v[92:95]
	v_mfma_f32_16x16x32_bf16 v[84:87], v[224:227], v[200:203], v[84:87]
	v_mfma_f32_16x16x32_bf16 v[76:79], v[216:219], v[208:211], v[76:79]
	v_mfma_f32_16x16x32_bf16 v[68:71], v[224:227], v[208:211], v[68:71]
	s_setprio 0
	s_mov_b32 m0, s60
	s_barrier
	ds_read_b128 v[180:183], v144 offset:49152
	ds_read_b128 v[184:187], v144 offset:50176
	ds_read_b128 v[188:191], v144 offset:51200
	ds_read_b128 v[192:195], v144 offset:52224
	ds_read_b128 v[196:199], v144 offset:53248
	ds_read_b128 v[200:203], v144 offset:54272
	ds_read_b128 v[204:207], v144 offset:55296
	ds_read_b128 v[208:211], v144 offset:56320
	global_load_lds_dwordx4 v138, s[56:57]
	s_mov_b32 m0, s61
	s_nop 0
	global_load_lds_dwordx4 v140, s[56:57]
	s_barrier
; __device__ __forceinline__ unsigned cvt_pk_bf16(float lo, float hi) { f32x2 v = {lo, hi}; bf16x2v b = __builtin_convertvector(v, bf16x2v); return __builtin_bit_cast(unsigned, b); }
; __device__ __forceinline__ float silu_f(float x) { return x * __builtin_amdgcn_rcpf(1.f + __expf(-x)); }
; #define PG8_STAGE(bufoff, gbase, voff) do { _Pragma("unroll") for (int _i = 0; _i < 2; ++_i) \
;         __builtin_amdgcn_global_load_lds((const unsigned*)((const char*)(gbase) + (voff)[_i]), (LAS unsigned*)(lds + (bufoff) + ldsw + _i * 8192), 16, 0, 0); } while (0)
; #define PG8_LDA(dst, b, h) do { _Pragma("unroll") for (int m = 0; m < 4; ++m) _Pragma("unroll") for (int k = 0; k < 2; ++k) dst[m][k] = *(const LAS bf16x8*)(lds + PG8_SA(b, h) + aoff + m * 2048 + k * 1024); } while (0)
;     __device__ __forceinline__ void operator()(const f32x4 (&acc)[2][2][4][2], const Unit& u, int wr, int wc, int fr, int fq) const {
;         const int row0 = u.pm * BM + wr * 64 + fr, col0 = u.pn * 128 + wc * 32 + 8 * fq;
; #pragma unroll
;         for (int ai = 0; ai < 2; ++ai)
; #pragma unroll
;             for (int m = 0; m < 4; ++m) {
;                 bf16_t* rowp = O + img_off(row0 + ai * HALF + m * 16, col0, D_FF / 64);
;                 const f32x4 g0 = acc[ai][0][m][0], g1 = acc[ai][0][m][1], u0 = acc[ai][1][m][0], u1 = acc[ai][1][m][1];
;                 u32x4 w;
;                 w.x = cvt_pk_bf16(silu_f(g0[0]) * u0[0], silu_f(g0[1]) * u0[1]); w.y = cvt_pk_bf16(silu_f(g0[2]) * u0[2], silu_f(g0[3]) * u0[3]);
;                 w.z = cvt_pk_bf16(silu_f(g1[0]) * u1[0], silu_f(g1[1]) * u1[1]); w.w = cvt_pk_bf16(silu_f(g1[2]) * u1[2], silu_f(g1[3]) * u1[3]);
;                 *(u32x4*)rowp = w;
; template <class Epi, class Sched, int LD>
; __device__ __forceinline__ void gemm_phase(LAS unsigned char* lds, const Gemm g, const Sched& S, const Epi& E) {
;     ...
;             PG8_WAIT_L(8); PG8_BAR; PG8_WAIT_L(0); PG8_MMA(0, 0, At, B0); PG8_BAR; PG8_SCHED;
;             PG8_LDB(B1, 1, 1); PG8_STAGE(PG8_SB(1, 0), b3, voffB);
;             PG8_BAR; PG8_WAIT_L(0); PG8_MMA(0, 1, At, B1); PG8_BAR;
;             PG8_LDA(At, 1, 1); PG8_STAGE(PG8_SA(1, 0), a3, voffA);
;             PG8_BAR; PG8_WAIT_L(0); PG8_MMA(1, 0, At, B0); PG8_BAR; PG8_SCHED;
;             PG8_STAGE(PG8_SB(1, 1), b3 + hstep, voffB);
;             PG8_WAIT_V(6); PG8_BAR; PG8_MMA(1, 1, At, B1); PG8_BAR;
	s_waitcnt lgkmcnt(0)
	s_setprio 1
	v_mfma_f32_16x16x32_bf16 v[64:67], v[146:149], v[180:183], v[64:67]
	v_mfma_f32_16x16x32_bf16 v[56:59], v[154:157], v[180:183], v[56:59]
	v_mfma_f32_16x16x32_bf16 v[48:51], v[146:149], v[188:191], v[48:51]
	v_mfma_f32_16x16x32_bf16 v[40:43], v[154:157], v[188:191], v[40:43]
	v_mfma_f32_16x16x32_bf16 v[32:35], v[146:149], v[196:199], v[32:35]
	v_mfma_f32_16x16x32_bf16 v[24:27], v[154:157], v[196:199], v[24:27]
	v_mfma_f32_16x16x32_bf16 v[16:19], v[146:149], v[204:207], v[16:19]
	v_mfma_f32_16x16x32_bf16 v[8:11], v[154:157], v[204:207], v[8:11]
	v_mfma_f32_16x16x32_bf16 v[64:67], v[150:153], v[184:187], v[64:67]
	v_mfma_f32_16x16x32_bf16 v[56:59], v[176:179], v[184:187], v[56:59]
	v_mfma_f32_16x16x32_bf16 v[48:51], v[150:153], v[192:195], v[48:51]
	v_mfma_f32_16x16x32_bf16 v[40:43], v[176:179], v[192:195], v[40:43]
	v_mfma_f32_16x16x32_bf16 v[32:35], v[150:153], v[200:203], v[32:35]
	v_mfma_f32_16x16x32_bf16 v[24:27], v[176:179], v[200:203], v[24:27]
	s_setprio 2
	s_barrier
	v_mfma_f32_16x16x32_bf16 v[16:19], v[150:153], v[208:211], v[16:19]
	v_mfma_f32_16x16x32_bf16 v[8:11], v[176:179], v[208:211], v[8:11]
	s_setprio 0
	s_add_u32 s4, s54, 0xc000
	s_addc_u32 s5, s55, 0
	s_add_i32 s54, s72, s28
	s_mov_b32 m0, s54
	s_nop 0
	global_load_lds_dwordx4 v138, s[4:5]
	s_add_i32 m0, s54, 0x2000
	s_nop 0
	global_load_lds_dwordx4 v140, s[4:5]
	s_waitcnt vmcnt(6)
	s_barrier
	s_setprio 1
	v_mfma_f32_16x16x32_bf16 v[60:63], v[212:215], v[180:183], v[60:63]
	v_mfma_f32_16x16x32_bf16 v[52:55], v[220:223], v[180:183], v[52:55]
	v_mfma_f32_16x16x32_bf16 v[44:47], v[212:215], v[188:191], v[44:47]
	v_mfma_f32_16x16x32_bf16 v[36:39], v[220:223], v[188:191], v[36:39]
	v_mfma_f32_16x16x32_bf16 v[28:31], v[212:215], v[196:199], v[28:31]
	v_mfma_f32_16x16x32_bf16 v[20:23], v[220:223], v[196:199], v[20:23]
	v_mfma_f32_16x16x32_bf16 v[12:15], v[212:215], v[204:207], v[12:15]
	v_mfma_f32_16x16x32_bf16 v[4:7], v[220:223], v[204:207], v[4:7]
	v_mfma_f32_16x16x32_bf16 v[60:63], v[216:219], v[184:187], v[60:63]
	v_mfma_f32_16x16x32_bf16 v[52:55], v[224:227], v[184:187], v[52:55]
	v_mfma_f32_16x16x32_bf16 v[44:47], v[216:219], v[192:195], v[44:47]
	v_mfma_f32_16x16x32_bf16 v[36:39], v[224:227], v[192:195], v[36:39]
	v_mfma_f32_16x16x32_bf16 v[28:31], v[216:219], v[200:203], v[28:31]
	v_mfma_f32_16x16x32_bf16 v[20:23], v[224:227], v[200:203], v[20:23]
	v_mfma_f32_16x16x32_bf16 v[12:15], v[216:219], v[208:211], v[12:15]
	v_mfma_f32_16x16x32_bf16 v[4:7], v[224:227], v[208:211], v[4:7]
	s_setprio 0
	s_add_i32 s70, s70, 2
	s_add_u32 s50, s50, 0x10000
	s_addc_u32 s51, s51, 0
	s_add_u32 s45, s45, 0x10000
	s_addc_u32 s47, s47, 0
	s_cmp_gt_u32 s70, 29
	s_barrier
	s_cbranch_scc0 .LBB0_899
	v_mul_f32_e32 v148, 0xbfb8aa3b, v128
	v_mul_f32_e32 v149, 0xbfb8aa3b, v129
	v_exp_f32_e32 v148, v148
	v_exp_f32_e32 v149, v149
	s_lshl_b32 s5, s69, 8
	s_add_i32 s5, s5, s58
	v_add_f32_e32 v148, 1.0, v148
	v_add_f32_e32 v149, 1.0, v149
	v_rcp_f32_e32 v148, v148
	v_rcp_f32_e32 v149, v149
	s_lshl_b32 s4, s68, 7
	s_or_b32 s4, s4, s59
	s_ashr_i32 s45, s5, 8
	v_pk_mul_f32 v[128:129], v[128:129], v[148:149]
	s_ashr_i32 s4, s4, 6
	v_pk_mul_f32 v[124:125], v[128:129], v[124:125]
	s_mulk_i32 s45, 0x58
	v_cvt_pk_bf16_f32 v124, v124, v125
	v_mul_f32_e32 v125, 0xbfb8aa3b, v130
	v_exp_f32_e32 v125, v125
	s_add_i32 s50, s45, s4
	s_ashr_i32 s51, s50, 31
	s_lshl_b64 s[50:51], s[50:51], 15
	v_add_f32_e32 v125, 1.0, v125
	v_rcp_f32_e32 v128, v125
	v_mul_f32_e32 v125, 0xbfb8aa3b, v131
	v_exp_f32_e32 v125, v125
	s_add_u32 s45, s16, s50
	s_addc_u32 s47, s17, s51
	s_lshl_b32 s50, s5, 7
	v_add_f32_e32 v125, 1.0, v125
	v_rcp_f32_e32 v129, v125
	s_and_b32 s50, s50, 0x4000
	s_add_u32 s50, s45, s50
	s_addc_u32 s51, s47, 0
	v_pk_mul_f32 v[128:129], v[130:131], v[128:129]
	s_or_b32 s45, s5, 16
	v_pk_mul_f32 v[126:127], v[128:129], v[126:127]
	s_lshr_b32 s45, s45, 3
	v_cvt_pk_bf16_f32 v125, v126, v127
	v_mul_f32_e32 v126, 0xbfb8aa3b, v120
	v_mul_f32_e32 v127, 0xbfb8aa3b, v121
	v_exp_f32_e32 v126, v126
	v_exp_f32_e32 v127, v127
	v_or_b32_e32 v145, s5, v137
	s_and_b32 s45, s45, 10
	v_add_f32_e32 v126, 1.0, v126
	v_add_f32_e32 v127, 1.0, v127
	v_rcp_f32_e32 v126, v126
	v_rcp_f32_e32 v127, v127
	v_lshlrev_b32_e32 v132, 6, v145
	v_lshlrev_b32_e32 v146, 2, v145
	s_or_b32 s45, s45, s64
	v_pk_mul_f32 v[120:121], v[120:121], v[126:127]
	v_and_or_b32 v132, v132, s15, v142
	v_pk_mul_f32 v[116:117], v[120:121], v[116:117]
	v_and_b32_e32 v146, 32, v146
	v_cvt_pk_bf16_f32 v126, v116, v117
	v_mul_f32_e32 v116, 0xbfb8aa3b, v122
	v_mul_f32_e32 v117, 0xbfb8aa3b, v123
	v_exp_f32_e32 v116, v116
	v_exp_f32_e32 v117, v117
	s_lshl_b32 s45, s45, 10
	v_bitop3_b32 v147, v132, s65, v146 bitop3:0xde
	v_add_f32_e32 v116, 1.0, v116
	v_add_f32_e32 v117, 1.0, v117
	v_rcp_f32_e32 v116, v116
	v_rcp_f32_e32 v117, v117
	s_and_b64 vcc, exec, s[42:43]
	s_mov_b32 s68, s44
	s_mov_b32 s69, s46
	v_pk_mul_f32 v[116:117], v[122:123], v[116:117]
	s_mov_b64 s[54:55], s[40:41]
	v_pk_mul_f32 v[116:117], v[116:117], v[118:119]
	v_bitop3_b32 v118, v132, s45, v146 bitop3:0xde
	v_cvt_pk_bf16_f32 v127, v116, v117
	v_mul_f32_e32 v116, 0xbfb8aa3b, v112
	v_mul_f32_e32 v117, 0xbfb8aa3b, v113
	v_exp_f32_e32 v116, v116
	v_exp_f32_e32 v117, v117
	s_or_b32 s45, s5, 32
	s_or_b32 s5, s5, 48
	v_add_f32_e32 v116, 1.0, v116
	v_add_f32_e32 v117, 1.0, v117
	v_rcp_f32_e32 v116, v116
	v_rcp_f32_e32 v117, v117
	s_lshr_b32 s45, s45, 3
	s_lshr_b32 s5, s5, 3
	s_and_b32 s45, s45, 12
	v_pk_mul_f32 v[112:113], v[112:113], v[116:117]
	s_and_b32 s5, s5, 14
	v_pk_mul_f32 v[108:109], v[112:113], v[108:109]
	s_or_b32 s45, s45, s64
	v_cvt_pk_bf16_f32 v108, v108, v109
; __device__ __forceinline__ unsigned cvt_pk_bf16(float lo, float hi) { f32x2 v = {lo, hi}; bf16x2v b = __builtin_convertvector(v, bf16x2v); return __builtin_bit_cast(unsigned, b); }
; __device__ __forceinline__ float silu_f(float x) { return x * __builtin_amdgcn_rcpf(1.f + __expf(-x)); }
;     __device__ __forceinline__ void operator()(const f32x4 (&acc)[2][2][4][2], const Unit& u, int wr, int wc, int fr, int fq) const {
;         const int row0 = u.pm * BM + wr * 64 + fr, col0 = u.pn * 128 + wc * 32 + 8 * fq;
; #pragma unroll
;         for (int ai = 0; ai < 2; ++ai)
; #pragma unroll
;             for (int m = 0; m < 4; ++m) {
;                 bf16_t* rowp = O + img_off(row0 + ai * HALF + m * 16, col0, D_FF / 64);
;                 const f32x4 g0 = acc[ai][0][m][0], g1 = acc[ai][0][m][1], u0 = acc[ai][1][m][0], u1 = acc[ai][1][m][1];
;                 u32x4 w;
;                 w.x = cvt_pk_bf16(silu_f(g0[0]) * u0[0], silu_f(g0[1]) * u0[1]); w.y = cvt_pk_bf16(silu_f(g0[2]) * u0[2], silu_f(g0[3]) * u0[3]);
;                 w.z = cvt_pk_bf16(silu_f(g1[0]) * u1[0], silu_f(g1[1]) * u1[1]); w.w = cvt_pk_bf16(silu_f(g1[2]) * u1[2], silu_f(g1[3]) * u1[3]);
;                 *(u32x4*)rowp = w;
	v_mul_f32_e32 v109, 0xbfb8aa3b, v114
	v_exp_f32_e32 v109, v109
	s_or_b32 s5, s5, s64
	s_lshl_b32 s45, s45, 10
	s_lshl_b32 s5, s5, 10
	v_add_f32_e32 v109, 1.0, v109
	v_rcp_f32_e32 v112, v109
	v_mul_f32_e32 v109, 0xbfb8aa3b, v115
	v_exp_f32_e32 v109, v109
	global_store_dwordx4 v147, v[124:127], s[50:51]
	v_add_f32_e32 v109, 1.0, v109
	v_rcp_f32_e32 v113, v109
	s_nop 0
	v_pk_mul_f32 v[112:113], v[114:115], v[112:113]
	s_nop 0
	v_pk_mul_f32 v[110:111], v[112:113], v[110:111]
	s_nop 0
	v_cvt_pk_bf16_f32 v109, v110, v111
	v_mul_f32_e32 v110, 0xbfb8aa3b, v104
	v_mul_f32_e32 v111, 0xbfb8aa3b, v105
	v_exp_f32_e32 v110, v110
	v_exp_f32_e32 v111, v111
	v_add_f32_e32 v110, 1.0, v110
	v_add_f32_e32 v111, 1.0, v111
	v_rcp_f32_e32 v110, v110
	v_rcp_f32_e32 v111, v111
	s_nop 0
	v_pk_mul_f32 v[104:105], v[104:105], v[110:111]
	s_nop 0
	v_pk_mul_f32 v[100:101], v[104:105], v[100:101]
	s_nop 0
	v_cvt_pk_bf16_f32 v110, v100, v101
	v_mul_f32_e32 v100, 0xbfb8aa3b, v106
	v_mul_f32_e32 v101, 0xbfb8aa3b, v107
	v_exp_f32_e32 v100, v100
	v_exp_f32_e32 v101, v101
	v_add_f32_e32 v100, 1.0, v100
	v_add_f32_e32 v101, 1.0, v101
	v_rcp_f32_e32 v100, v100
	v_rcp_f32_e32 v101, v101
	s_nop 0
	v_pk_mul_f32 v[100:101], v[106:107], v[100:101]
	s_nop 0
	v_pk_mul_f32 v[100:101], v[100:101], v[102:103]
	v_bitop3_b32 v102, v132, s45, v146 bitop3:0xde
	v_cvt_pk_bf16_f32 v111, v100, v101
	v_mul_f32_e32 v100, 0xbfb8aa3b, v96
	v_mul_f32_e32 v101, 0xbfb8aa3b, v97
	v_exp_f32_e32 v100, v100
	v_exp_f32_e32 v101, v101
	global_store_dwordx4 v118, v[108:111], s[50:51]
	v_add_f32_e32 v100, 1.0, v100
	v_add_f32_e32 v101, 1.0, v101
	v_rcp_f32_e32 v100, v100
	v_rcp_f32_e32 v101, v101
	s_nop 0
	v_pk_mul_f32 v[96:97], v[96:97], v[100:101]
	s_nop 0
	v_pk_mul_f32 v[92:93], v[96:97], v[92:93]
	s_nop 0
	v_cvt_pk_bf16_f32 v92, v92, v93
	v_mul_f32_e32 v93, 0xbfb8aa3b, v98
	v_exp_f32_e32 v93, v93
	s_nop 0
	v_add_f32_e32 v93, 1.0, v93
	v_rcp_f32_e32 v96, v93
	v_mul_f32_e32 v93, 0xbfb8aa3b, v99
	v_exp_f32_e32 v93, v93
	s_nop 0
	v_add_f32_e32 v93, 1.0, v93
	v_rcp_f32_e32 v97, v93
	s_nop 0
	v_pk_mul_f32 v[96:97], v[98:99], v[96:97]
	s_nop 0
	v_pk_mul_f32 v[94:95], v[96:97], v[94:95]
	s_nop 0
	v_cvt_pk_bf16_f32 v93, v94, v95
	v_mul_f32_e32 v94, 0xbfb8aa3b, v88
	v_mul_f32_e32 v95, 0xbfb8aa3b, v89
	v_exp_f32_e32 v94, v94
	v_exp_f32_e32 v95, v95
	v_add_f32_e32 v94, 1.0, v94
	v_add_f32_e32 v95, 1.0, v95
	v_rcp_f32_e32 v94, v94
	v_rcp_f32_e32 v95, v95
	s_nop 0
	v_pk_mul_f32 v[88:89], v[88:89], v[94:95]
	s_nop 0
	v_pk_mul_f32 v[84:85], v[88:89], v[84:85]
	s_nop 0
	v_cvt_pk_bf16_f32 v94, v84, v85
	v_mul_f32_e32 v84, 0xbfb8aa3b, v90
	v_mul_f32_e32 v85, 0xbfb8aa3b, v91
	v_exp_f32_e32 v84, v84
	v_exp_f32_e32 v85, v85
	v_add_f32_e32 v84, 1.0, v84
	v_add_f32_e32 v85, 1.0, v85
	v_rcp_f32_e32 v84, v84
	v_rcp_f32_e32 v85, v85
	s_nop 0
	v_pk_mul_f32 v[84:85], v[90:91], v[84:85]
	s_nop 0
	v_pk_mul_f32 v[84:85], v[84:85], v[86:87]
	v_bitop3_b32 v86, v132, s5, v146 bitop3:0xde
	v_cvt_pk_bf16_f32 v95, v84, v85
	v_mul_f32_e32 v84, 0xbfb8aa3b, v80
	v_mul_f32_e32 v85, 0xbfb8aa3b, v81
	v_exp_f32_e32 v84, v84
	v_exp_f32_e32 v85, v85
	global_store_dwordx4 v102, v[92:95], s[50:51]
	v_add_f32_e32 v84, 1.0, v84
	v_add_f32_e32 v85, 1.0, v85
	v_rcp_f32_e32 v84, v84
	v_rcp_f32_e32 v85, v85
	s_nop 0
	v_pk_mul_f32 v[80:81], v[80:81], v[84:85]
	s_nop 0
	v_pk_mul_f32 v[76:77], v[80:81], v[76:77]
	s_nop 0
	v_cvt_pk_bf16_f32 v76, v76, v77
	v_mul_f32_e32 v77, 0xbfb8aa3b, v82
	v_exp_f32_e32 v77, v77
	s_nop 0
	v_add_f32_e32 v77, 1.0, v77
	v_rcp_f32_e32 v80, v77
	v_mul_f32_e32 v77, 0xbfb8aa3b, v83
	v_exp_f32_e32 v77, v77
	s_nop 0
	v_add_f32_e32 v77, 1.0, v77
	v_rcp_f32_e32 v81, v77
	s_nop 0
	v_pk_mul_f32 v[80:81], v[82:83], v[80:81]
	s_nop 0
	v_pk_mul_f32 v[78:79], v[80:81], v[78:79]
	s_nop 0
	v_cvt_pk_bf16_f32 v77, v78, v79
	v_mul_f32_e32 v78, 0xbfb8aa3b, v72
	v_mul_f32_e32 v79, 0xbfb8aa3b, v73
	v_exp_f32_e32 v78, v78
	v_exp_f32_e32 v79, v79
	v_add_f32_e32 v78, 1.0, v78
	v_add_f32_e32 v79, 1.0, v79
	v_rcp_f32_e32 v78, v78
	v_rcp_f32_e32 v79, v79
	s_nop 0
	v_pk_mul_f32 v[72:73], v[72:73], v[78:79]
	s_nop 0
	v_pk_mul_f32 v[68:69], v[72:73], v[68:69]
	v_mul_f32_e32 v73, 0xbfb8aa3b, v65
	v_cvt_pk_bf16_f32 v78, v68, v69
	v_mul_f32_e32 v68, 0xbfb8aa3b, v74
	v_mul_f32_e32 v69, 0xbfb8aa3b, v75
	v_exp_f32_e32 v68, v68
	v_exp_f32_e32 v69, v69
	v_exp_f32_e32 v73, v73
	v_add_f32_e32 v68, 1.0, v68
	v_add_f32_e32 v69, 1.0, v69
	v_rcp_f32_e32 v68, v68
	v_rcp_f32_e32 v69, v69
	v_add_f32_e32 v73, 1.0, v73
	v_rcp_f32_e32 v73, v73
	v_pk_mul_f32 v[68:69], v[74:75], v[68:69]
	s_nop 0
	v_pk_mul_f32 v[68:69], v[68:69], v[70:71]
	v_add_u32_e32 v70, 0x80, v145
	v_lshlrev_b32_e32 v71, 6, v70
	v_lshlrev_b32_e32 v72, 2, v70
	v_and_or_b32 v71, v71, s15, v142
	v_and_b32_e32 v72, 32, v72
	v_bitop3_b32 v132, v71, s65, v72 bitop3:0xde
	v_mul_f32_e32 v72, 0xbfb8aa3b, v64
	v_exp_f32_e32 v72, v72
	v_cvt_pk_bf16_f32 v79, v68, v69
	v_lshrrev_b32_e32 v68, 8, v70
	v_mov_b32_e32 v69, s4
	v_add_f32_e32 v72, 1.0, v72
	v_rcp_f32_e32 v72, v72
	s_movk_i32 s4, 0x58
	v_mad_i32_i24 v68, v68, s4, v69
	v_ashrrev_i32_e32 v69, 31, v68
	v_pk_mul_f32 v[64:65], v[64:65], v[72:73]
	v_lshlrev_b64 v[68:69], 15, v[68:69]
	v_pk_mul_f32 v[60:61], v[64:65], v[60:61]
	v_lshlrev_b32_e32 v70, 7, v70
	v_cvt_pk_bf16_f32 v60, v60, v61
	v_mul_f32_e32 v61, 0xbfb8aa3b, v66
	v_exp_f32_e32 v61, v61
	v_lshl_add_u64 v[68:69], s[16:17], 0, v[68:69]
	v_and_b32_e32 v70, 0x4000, v70
	v_mov_b32_e32 v71, v133
	v_add_f32_e32 v61, 1.0, v61
	v_rcp_f32_e32 v64, v61
	v_mul_f32_e32 v61, 0xbfb8aa3b, v67
	v_exp_f32_e32 v61, v61
	v_lshl_add_u64 v[70:71], v[68:69], 0, v[70:71]
	v_lshl_add_u64 v[70:71], v[70:71], 0, v[132:133]
; __device__ __forceinline__ unsigned cvt_pk_bf16(float lo, float hi) { f32x2 v = {lo, hi}; bf16x2v b = __builtin_convertvector(v, bf16x2v); return __builtin_bit_cast(unsigned, b); }
; __device__ __forceinline__ float silu_f(float x) { return x * __builtin_amdgcn_rcpf(1.f + __expf(-x)); }
;     __device__ __forceinline__ void operator()(const f32x4 (&acc)[2][2][4][2], const Unit& u, int wr, int wc, int fr, int fq) const {
;         const int row0 = u.pm * BM + wr * 64 + fr, col0 = u.pn * 128 + wc * 32 + 8 * fq;
; #pragma unroll
;         for (int ai = 0; ai < 2; ++ai)
; #pragma unroll
;             for (int m = 0; m < 4; ++m) {
;                 bf16_t* rowp = O + img_off(row0 + ai * HALF + m * 16, col0, D_FF / 64);
;                 const f32x4 g0 = acc[ai][0][m][0], g1 = acc[ai][0][m][1], u0 = acc[ai][1][m][0], u1 = acc[ai][1][m][1];
;                 u32x4 w;
;                 w.x = cvt_pk_bf16(silu_f(g0[0]) * u0[0], silu_f(g0[1]) * u0[1]); w.y = cvt_pk_bf16(silu_f(g0[2]) * u0[2], silu_f(g0[3]) * u0[3]);
;                 w.z = cvt_pk_bf16(silu_f(g1[0]) * u1[0], silu_f(g1[1]) * u1[1]); w.w = cvt_pk_bf16(silu_f(g1[2]) * u1[2], silu_f(g1[3]) * u1[3]);
;                 *(u32x4*)rowp = w;
	s_mov_b64 s[4:5], s[48:49]
	v_add_f32_e32 v61, 1.0, v61
	v_rcp_f32_e32 v65, v61
	global_store_dwordx4 v86, v[76:79], s[50:51]
	v_pk_mul_f32 v[64:65], v[66:67], v[64:65]
	s_nop 0
	v_pk_mul_f32 v[62:63], v[64:65], v[62:63]
	s_nop 0
	v_cvt_pk_bf16_f32 v61, v62, v63
	v_mul_f32_e32 v62, 0xbfb8aa3b, v56
	v_mul_f32_e32 v63, 0xbfb8aa3b, v57
	v_exp_f32_e32 v62, v62
	v_exp_f32_e32 v63, v63
	v_add_f32_e32 v62, 1.0, v62
	v_add_f32_e32 v63, 1.0, v63
	v_rcp_f32_e32 v62, v62
	v_rcp_f32_e32 v63, v63
	s_nop 0
	v_pk_mul_f32 v[56:57], v[56:57], v[62:63]
	s_nop 0
	v_pk_mul_f32 v[52:53], v[56:57], v[52:53]
	s_nop 0
	v_cvt_pk_bf16_f32 v62, v52, v53
	v_mul_f32_e32 v52, 0xbfb8aa3b, v58
	v_mul_f32_e32 v53, 0xbfb8aa3b, v59
	v_exp_f32_e32 v52, v52
	v_exp_f32_e32 v53, v53
	v_add_f32_e32 v52, 1.0, v52
	v_add_f32_e32 v53, 1.0, v53
	v_rcp_f32_e32 v52, v52
	v_rcp_f32_e32 v53, v53
	s_nop 0
	v_pk_mul_f32 v[52:53], v[58:59], v[52:53]
	s_nop 0
	v_pk_mul_f32 v[52:53], v[52:53], v[54:55]
	s_nop 0
	v_cvt_pk_bf16_f32 v63, v52, v53
	v_add_u32_e32 v52, 0x90, v145
	v_lshrrev_b32_e32 v54, 3, v52
	v_lshlrev_b32_e32 v53, 6, v52
	v_and_or_b32 v54, v54, 10, s64
	v_lshlrev_b32_e32 v55, 2, v52
	v_and_or_b32 v53, v53, s15, v142
	v_lshlrev_b32_e32 v54, 10, v54
	v_and_b32_e32 v55, 32, v55
	v_bitop3_b32 v132, v53, v54, v55 bitop3:0xde
	v_mul_f32_e32 v54, 0xbfb8aa3b, v48
	v_mul_f32_e32 v55, 0xbfb8aa3b, v49
	v_exp_f32_e32 v54, v54
	v_exp_f32_e32 v55, v55
	v_lshlrev_b32_e32 v52, 7, v52
	v_and_b32_e32 v52, 0x4000, v52
	v_add_f32_e32 v54, 1.0, v54
	v_add_f32_e32 v55, 1.0, v55
	v_rcp_f32_e32 v54, v54
	v_rcp_f32_e32 v55, v55
	v_mov_b32_e32 v53, v133
	v_lshl_add_u64 v[52:53], v[68:69], 0, v[52:53]
	v_lshl_add_u64 v[52:53], v[52:53], 0, v[132:133]
	v_pk_mul_f32 v[48:49], v[48:49], v[54:55]
	global_store_dwordx4 v[70:71], v[60:63], off
	v_pk_mul_f32 v[44:45], v[48:49], v[44:45]
	s_nop 0
	v_cvt_pk_bf16_f32 v44, v44, v45
	v_mul_f32_e32 v45, 0xbfb8aa3b, v50
	v_exp_f32_e32 v45, v45
	s_nop 0
	v_add_f32_e32 v45, 1.0, v45
	v_rcp_f32_e32 v48, v45
	v_mul_f32_e32 v45, 0xbfb8aa3b, v51
	v_exp_f32_e32 v45, v45
	s_nop 0
	v_add_f32_e32 v45, 1.0, v45
	v_rcp_f32_e32 v49, v45
	s_nop 0
	v_pk_mul_f32 v[48:49], v[50:51], v[48:49]
	s_nop 0
	v_pk_mul_f32 v[46:47], v[48:49], v[46:47]
	s_nop 0
	v_cvt_pk_bf16_f32 v45, v46, v47
	v_mul_f32_e32 v46, 0xbfb8aa3b, v40
	v_mul_f32_e32 v47, 0xbfb8aa3b, v41
	v_exp_f32_e32 v46, v46
	v_exp_f32_e32 v47, v47
	v_add_f32_e32 v46, 1.0, v46
	v_add_f32_e32 v47, 1.0, v47
	v_rcp_f32_e32 v46, v46
	v_rcp_f32_e32 v47, v47
	s_nop 0
	v_pk_mul_f32 v[40:41], v[40:41], v[46:47]
	s_nop 0
	v_pk_mul_f32 v[36:37], v[40:41], v[36:37]
	s_nop 0
	v_cvt_pk_bf16_f32 v46, v36, v37
	v_mul_f32_e32 v36, 0xbfb8aa3b, v42
	v_mul_f32_e32 v37, 0xbfb8aa3b, v43
	v_exp_f32_e32 v36, v36
	v_exp_f32_e32 v37, v37
	v_add_f32_e32 v36, 1.0, v36
	v_add_f32_e32 v37, 1.0, v37
	v_rcp_f32_e32 v36, v36
	v_rcp_f32_e32 v37, v37
	s_nop 0
	v_pk_mul_f32 v[36:37], v[42:43], v[36:37]
	s_nop 0
	v_pk_mul_f32 v[36:37], v[36:37], v[38:39]
	s_nop 0
	v_cvt_pk_bf16_f32 v47, v36, v37
	v_add_u32_e32 v36, 0xa0, v145
	v_lshrrev_b32_e32 v38, 3, v36
	v_lshlrev_b32_e32 v37, 6, v36
	v_and_or_b32 v38, v38, 12, s64
	v_lshlrev_b32_e32 v39, 2, v36
	v_and_or_b32 v37, v37, s15, v142
	v_lshlrev_b32_e32 v38, 10, v38
	v_and_b32_e32 v39, 32, v39
	v_bitop3_b32 v132, v37, v38, v39 bitop3:0xde
	v_mul_f32_e32 v38, 0xbfb8aa3b, v32
	v_mul_f32_e32 v39, 0xbfb8aa3b, v33
	v_exp_f32_e32 v38, v38
	v_exp_f32_e32 v39, v39
	v_lshlrev_b32_e32 v36, 7, v36
	v_and_b32_e32 v36, 0x4000, v36
	v_add_f32_e32 v38, 1.0, v38
	v_add_f32_e32 v39, 1.0, v39
	v_rcp_f32_e32 v38, v38
; __device__ __forceinline__ unsigned cvt_pk_bf16(float lo, float hi) { f32x2 v = {lo, hi}; bf16x2v b = __builtin_convertvector(v, bf16x2v); return __builtin_bit_cast(unsigned, b); }
; __device__ __forceinline__ float silu_f(float x) { return x * __builtin_amdgcn_rcpf(1.f + __expf(-x)); }
; #define PG8_WAIT_V(n) asm volatile("s_waitcnt vmcnt(" #n ")" ::: "memory")
; #define PG8_BAR __builtin_amdgcn_s_barrier()
;     __device__ __forceinline__ void operator()(const f32x4 (&acc)[2][2][4][2], const Unit& u, int wr, int wc, int fr, int fq) const {
;         const int row0 = u.pm * BM + wr * 64 + fr, col0 = u.pn * 128 + wc * 32 + 8 * fq;
; #pragma unroll
;         for (int ai = 0; ai < 2; ++ai)
; #pragma unroll
;             for (int m = 0; m < 4; ++m) {
;                 bf16_t* rowp = O + img_off(row0 + ai * HALF + m * 16, col0, D_FF / 64);
;                 const f32x4 g0 = acc[ai][0][m][0], g1 = acc[ai][0][m][1], u0 = acc[ai][1][m][0], u1 = acc[ai][1][m][1];
;                 u32x4 w;
;                 w.x = cvt_pk_bf16(silu_f(g0[0]) * u0[0], silu_f(g0[1]) * u0[1]); w.y = cvt_pk_bf16(silu_f(g0[2]) * u0[2], silu_f(g0[3]) * u0[3]);
;                 w.z = cvt_pk_bf16(silu_f(g1[0]) * u1[0], silu_f(g1[1]) * u1[1]); w.w = cvt_pk_bf16(silu_f(g1[2]) * u1[2], silu_f(g1[3]) * u1[3]);
;                 *(u32x4*)rowp = w;
; template <class Epi, class Sched, int LD>
; __device__ __forceinline__ void gemm_phase(LAS unsigned char* lds, const Gemm g, const Sched& S, const Epi& E) {
;     ...
;         E(acc, cur, wr, wc, fr, fq);
;         if (!has_next) break;
; #pragma unroll
;         for (int a = 0; a < 2; ++a)
; #pragma unroll
;             for (int b = 0; b < 2; ++b)
; #pragma unroll
;                 for (int m = 0; m < 4; ++m)
; #pragma unroll
;                     for (int n = 0; n < 2; ++n) acc[a][b][m][n] = (f32x4){0.f, 0.f, 0.f, 0.f};
;         cur = nxt; cA = nA; cB = nB; ++ui;
;     }
;     PG8_WAIT_V(0);
;     if (wr == 0) PG8_BAR;
;     PG8_BAR;
	v_rcp_f32_e32 v39, v39
	v_mov_b32_e32 v37, v133
	v_lshl_add_u64 v[36:37], v[68:69], 0, v[36:37]
	v_lshl_add_u64 v[36:37], v[36:37], 0, v[132:133]
	v_pk_mul_f32 v[32:33], v[32:33], v[38:39]
	global_store_dwordx4 v[52:53], v[44:47], off
	v_pk_mul_f32 v[28:29], v[32:33], v[28:29]
	s_nop 0
	v_cvt_pk_bf16_f32 v28, v28, v29
	v_mul_f32_e32 v29, 0xbfb8aa3b, v34
	v_exp_f32_e32 v29, v29
	s_nop 0
	v_add_f32_e32 v29, 1.0, v29
	v_rcp_f32_e32 v32, v29
	v_mul_f32_e32 v29, 0xbfb8aa3b, v35
	v_exp_f32_e32 v29, v29
	s_nop 0
	v_add_f32_e32 v29, 1.0, v29
	v_rcp_f32_e32 v33, v29
	s_nop 0
	v_pk_mul_f32 v[32:33], v[34:35], v[32:33]
	s_nop 0
	v_pk_mul_f32 v[30:31], v[32:33], v[30:31]
	s_nop 0
	v_cvt_pk_bf16_f32 v29, v30, v31
	v_mul_f32_e32 v30, 0xbfb8aa3b, v24
	v_mul_f32_e32 v31, 0xbfb8aa3b, v25
	v_exp_f32_e32 v30, v30
	v_exp_f32_e32 v31, v31
	v_add_f32_e32 v30, 1.0, v30
	v_add_f32_e32 v31, 1.0, v31
	v_rcp_f32_e32 v30, v30
	v_rcp_f32_e32 v31, v31
	s_nop 0
	v_pk_mul_f32 v[24:25], v[24:25], v[30:31]
	s_nop 0
	v_pk_mul_f32 v[20:21], v[24:25], v[20:21]
	s_nop 0
	v_cvt_pk_bf16_f32 v30, v20, v21
	v_mul_f32_e32 v20, 0xbfb8aa3b, v26
	v_mul_f32_e32 v21, 0xbfb8aa3b, v27
	v_exp_f32_e32 v20, v20
	v_exp_f32_e32 v21, v21
	v_add_f32_e32 v20, 1.0, v20
	v_add_f32_e32 v21, 1.0, v21
	v_rcp_f32_e32 v20, v20
	v_rcp_f32_e32 v21, v21
	s_nop 0
	v_pk_mul_f32 v[20:21], v[26:27], v[20:21]
	s_nop 0
	v_pk_mul_f32 v[20:21], v[20:21], v[22:23]
	s_nop 0
	v_cvt_pk_bf16_f32 v31, v20, v21
	v_add_u32_e32 v20, 0xb0, v145
	v_lshrrev_b32_e32 v22, 3, v20
	v_lshlrev_b32_e32 v21, 6, v20
	v_and_or_b32 v22, v22, 14, s64
	v_lshlrev_b32_e32 v23, 2, v20
	v_and_or_b32 v21, v21, s15, v142
	v_lshlrev_b32_e32 v22, 10, v22
	v_and_b32_e32 v23, 32, v23
	v_bitop3_b32 v132, v21, v22, v23 bitop3:0xde
	v_mul_f32_e32 v22, 0xbfb8aa3b, v16
	v_mul_f32_e32 v23, 0xbfb8aa3b, v17
	v_exp_f32_e32 v22, v22
	v_exp_f32_e32 v23, v23
	v_lshlrev_b32_e32 v20, 7, v20
	v_and_b32_e32 v20, 0x4000, v20
	v_add_f32_e32 v22, 1.0, v22
	v_add_f32_e32 v23, 1.0, v23
	v_rcp_f32_e32 v22, v22
	v_rcp_f32_e32 v23, v23
	v_mov_b32_e32 v21, v133
	v_lshl_add_u64 v[20:21], v[68:69], 0, v[20:21]
	v_lshl_add_u64 v[20:21], v[20:21], 0, v[132:133]
	v_pk_mul_f32 v[16:17], v[16:17], v[22:23]
	global_store_dwordx4 v[36:37], v[28:31], off
	v_pk_mul_f32 v[12:13], v[16:17], v[12:13]
	s_nop 0
	v_cvt_pk_bf16_f32 v12, v12, v13
	v_mul_f32_e32 v13, 0xbfb8aa3b, v18
	v_exp_f32_e32 v13, v13
	s_nop 0
	v_add_f32_e32 v13, 1.0, v13
	v_rcp_f32_e32 v16, v13
	v_mul_f32_e32 v13, 0xbfb8aa3b, v19
	v_exp_f32_e32 v13, v13
	s_nop 0
	v_add_f32_e32 v13, 1.0, v13
	v_rcp_f32_e32 v17, v13
	s_nop 0
	v_pk_mul_f32 v[16:17], v[18:19], v[16:17]
	s_nop 0
	v_pk_mul_f32 v[14:15], v[16:17], v[14:15]
	s_nop 0
	v_cvt_pk_bf16_f32 v13, v14, v15
	v_mul_f32_e32 v14, 0xbfb8aa3b, v8
	v_mul_f32_e32 v15, 0xbfb8aa3b, v9
	v_exp_f32_e32 v14, v14
	v_exp_f32_e32 v15, v15
	v_add_f32_e32 v14, 1.0, v14
	v_add_f32_e32 v15, 1.0, v15
	v_rcp_f32_e32 v14, v14
	v_rcp_f32_e32 v15, v15
	s_nop 0
	v_pk_mul_f32 v[8:9], v[8:9], v[14:15]
	s_nop 0
	v_pk_mul_f32 v[4:5], v[8:9], v[4:5]
	s_nop 0
	v_cvt_pk_bf16_f32 v14, v4, v5
	v_mul_f32_e32 v4, 0xbfb8aa3b, v10
	v_mul_f32_e32 v5, 0xbfb8aa3b, v11
	v_exp_f32_e32 v4, v4
	v_exp_f32_e32 v5, v5
	v_add_f32_e32 v4, 1.0, v4
	v_add_f32_e32 v5, 1.0, v5
	v_rcp_f32_e32 v4, v4
	v_rcp_f32_e32 v5, v5
	s_nop 0
	v_pk_mul_f32 v[4:5], v[10:11], v[4:5]
	s_nop 0
	v_pk_mul_f32 v[4:5], v[4:5], v[6:7]
	s_nop 0
	v_cvt_pk_bf16_f32 v15, v4, v5
	global_store_dwordx4 v[20:21], v[12:15], off
	s_cbranch_vccz .LBB0_892
	s_waitcnt vmcnt(0)
	s_cmpk_gt_u32 s2, 0xff
	s_cbranch_scc1 .LBB0_903
	s_barrier
